# epilogue de-serialisation: the rstd-scaled GEMM epilogue (SB q/k projections) prefetches the row statistics of six row groups at once into dead MFMA fragment registers instead of a dependent load + vm
# speedup vs baseline: 1.0076x; 1.0055x over previous
.LBB0_83:
	s_add_u32 s4, s0, 0xfff80080
	s_addc_u32 s5, s1, -1
	s_add_i32 s26, 16, 0x10000
	v_add_u32_e32 v151, s26, v148
	ds_read_b128 v[134:137], v151
	ds_read_b128 v[162:165], v151 offset:1024
	ds_read_b128 v[166:169], v151 offset:2048
	ds_read_b128 v[170:173], v151 offset:3072
	s_cmp_eq_u32 s45, 28
	s_cselect_b32 s13, s3, s5
	s_cselect_b32 s12, s15, s4
	s_cselect_b32 s5, s11, s43
	s_cselect_b32 s4, s16, s30
	v_lshl_add_u64 v[152:153], s[0:1], 0, v[130:131]
	s_add_i32 m0, s89, 0xc000
	ds_read_b128 v[174:177], v150
	ds_read_b128 v[186:189], v150 offset:1024
	ds_read_b128 v[190:193], v150 offset:2048
	ds_read_b128 v[194:197], v150 offset:3072
	ds_read_b128 v[198:201], v150 offset:4096
	ds_read_b128 v[202:205], v150 offset:5120
	ds_read_b128 v[206:209], v150 offset:6144
	ds_read_b128 v[210:213], v150 offset:7168
	global_load_lds_dwordx4 v[152:153], off
	v_lshl_add_u64 v[152:153], s[0:1], 0, v[132:133]
	s_add_i32 m0, s89, 0xe000
	s_nop 0
	global_load_lds_dwordx4 v[152:153], off
	s_waitcnt lgkmcnt(8)
	s_barrier
	s_waitcnt lgkmcnt(0)
	s_setprio 1
	s_waitcnt lgkmcnt(0)
	v_mfma_f32_16x16x32_bf16 v[126:129], v[134:137], v[174:177], v[126:129]
	v_mfma_f32_16x16x32_bf16 v[122:125], v[166:169], v[174:177], v[122:125]
	v_mfma_f32_16x16x32_bf16 v[110:113], v[134:137], v[190:193], v[110:113]
	v_mfma_f32_16x16x32_bf16 v[106:109], v[166:169], v[190:193], v[106:109]
	v_mfma_f32_16x16x32_bf16 v[94:97], v[134:137], v[198:201], v[94:97]
	v_mfma_f32_16x16x32_bf16 v[90:93], v[166:169], v[198:201], v[90:93]
	v_mfma_f32_16x16x32_bf16 v[78:81], v[134:137], v[206:209], v[78:81]
	v_mfma_f32_16x16x32_bf16 v[74:77], v[166:169], v[206:209], v[74:77]
	v_mfma_f32_16x16x32_bf16 v[126:129], v[162:165], v[186:189], v[126:129]
	v_mfma_f32_16x16x32_bf16 v[122:125], v[170:173], v[186:189], v[122:125]
	v_mfma_f32_16x16x32_bf16 v[110:113], v[162:165], v[194:197], v[110:113]
	v_mfma_f32_16x16x32_bf16 v[106:109], v[170:173], v[194:197], v[106:109]
	v_mfma_f32_16x16x32_bf16 v[94:97], v[162:165], v[202:205], v[94:97]
	v_mfma_f32_16x16x32_bf16 v[90:93], v[170:173], v[202:205], v[90:93]
	v_mfma_f32_16x16x32_bf16 v[78:81], v[162:165], v[210:213], v[78:81]
	v_mfma_f32_16x16x32_bf16 v[74:77], v[170:173], v[210:213], v[74:77]
	s_setprio 0
	s_barrier
	s_add_i32 s27, 16, 0x14000
	s_add_i32 s26, s26, s18
	v_add_u32_e32 v151, s27, v148
	v_lshl_add_u64 v[152:153], s[4:5], 0, v[156:157]
	s_mov_b32 m0, s26
	ds_read_b128 v[214:217], v151
	ds_read_b128 v[218:221], v151 offset:1024
	ds_read_b128 v[222:225], v151 offset:2048
	ds_read_b128 v[226:229], v151 offset:3072
	global_load_lds_dwordx4 v[152:153], off
	v_lshl_add_u64 v[178:179], s[4:5], 0, v[160:161]
	s_add_i32 m0, s26, 0x2000
	s_nop 0
	global_load_lds_dwordx4 v[178:179], off
	s_barrier
	s_waitcnt lgkmcnt(0)
	s_setprio 1
	s_waitcnt lgkmcnt(0)
	v_mfma_f32_16x16x32_bf16 v[118:121], v[214:217], v[174:177], v[118:121]
	v_mfma_f32_16x16x32_bf16 v[114:117], v[222:225], v[174:177], v[114:117]
	v_mfma_f32_16x16x32_bf16 v[102:105], v[214:217], v[190:193], v[102:105]
	v_mfma_f32_16x16x32_bf16 v[98:101], v[222:225], v[190:193], v[98:101]
	v_mfma_f32_16x16x32_bf16 v[86:89], v[214:217], v[198:201], v[86:89]
	v_mfma_f32_16x16x32_bf16 v[82:85], v[222:225], v[198:201], v[82:85]
	v_mfma_f32_16x16x32_bf16 v[70:73], v[214:217], v[206:209], v[70:73]
	v_mfma_f32_16x16x32_bf16 v[66:69], v[222:225], v[206:209], v[66:69]
	v_mfma_f32_16x16x32_bf16 v[118:121], v[218:221], v[186:189], v[118:121]
	v_mfma_f32_16x16x32_bf16 v[114:117], v[226:229], v[186:189], v[114:117]
	v_mfma_f32_16x16x32_bf16 v[102:105], v[218:221], v[194:197], v[102:105]
	v_mfma_f32_16x16x32_bf16 v[98:101], v[226:229], v[194:197], v[98:101]
	v_mfma_f32_16x16x32_bf16 v[86:89], v[218:221], v[202:205], v[86:89]
	v_mfma_f32_16x16x32_bf16 v[82:85], v[226:229], v[202:205], v[82:85]
	v_mfma_f32_16x16x32_bf16 v[70:73], v[218:221], v[210:213], v[70:73]
	v_mfma_f32_16x16x32_bf16 v[66:69], v[226:229], v[210:213], v[66:69]
	s_setprio 0
	s_mov_b32 m0, s89
	v_lshl_add_u64 v[230:231], s[12:13], 0, v[154:155]
	s_barrier
	ds_read_b128 v[174:177], v150 offset:16384
	ds_read_b128 v[186:189], v150 offset:17408
	ds_read_b128 v[190:193], v150 offset:18432
	ds_read_b128 v[194:197], v150 offset:19456
	ds_read_b128 v[198:201], v150 offset:20480
	ds_read_b128 v[202:205], v150 offset:21504
	ds_read_b128 v[206:209], v150 offset:22528
	ds_read_b128 v[210:213], v150 offset:23552
	global_load_lds_dwordx4 v[230:231], off
	v_lshl_add_u64 v[242:243], s[12:13], 0, v[158:159]
	s_mov_b32 m0, s64
	s_nop 0
	global_load_lds_dwordx4 v[242:243], off
	s_barrier
	s_waitcnt lgkmcnt(0)
	s_setprio 1
	s_waitcnt lgkmcnt(0)
	v_mfma_f32_16x16x32_bf16 v[62:65], v[134:137], v[174:177], v[62:65]
	v_mfma_f32_16x16x32_bf16 v[58:61], v[166:169], v[174:177], v[58:61]
	v_mfma_f32_16x16x32_bf16 v[46:49], v[134:137], v[190:193], v[46:49]
	v_mfma_f32_16x16x32_bf16 v[42:45], v[166:169], v[190:193], v[42:45]
	v_mfma_f32_16x16x32_bf16 v[30:33], v[134:137], v[198:201], v[30:33]
	v_mfma_f32_16x16x32_bf16 v[26:29], v[166:169], v[198:201], v[26:29]
	v_mfma_f32_16x16x32_bf16 v[14:17], v[134:137], v[206:209], v[14:17]
	v_mfma_f32_16x16x32_bf16 v[10:13], v[166:169], v[206:209], v[10:13]
	v_mfma_f32_16x16x32_bf16 v[62:65], v[162:165], v[186:189], v[62:65]
	v_mfma_f32_16x16x32_bf16 v[58:61], v[170:173], v[186:189], v[58:61]
	v_mfma_f32_16x16x32_bf16 v[46:49], v[162:165], v[194:197], v[46:49]
	v_mfma_f32_16x16x32_bf16 v[42:45], v[170:173], v[194:197], v[42:45]
	v_mfma_f32_16x16x32_bf16 v[30:33], v[162:165], v[202:205], v[30:33]
	v_mfma_f32_16x16x32_bf16 v[26:29], v[170:173], v[202:205], v[26:29]
	v_mfma_f32_16x16x32_bf16 v[14:17], v[162:165], v[210:213], v[14:17]
	v_mfma_f32_16x16x32_bf16 v[10:13], v[170:173], v[210:213], v[10:13]
	s_setprio 0
	s_barrier
	s_add_u32 vcc_lo, s4, 0x80000
	s_addc_u32 vcc_hi, s5, 0
	s_add_i32 s26, s27, s18
	v_lshl_add_u64 v[134:135], vcc, 0, v[156:157]
	s_mov_b32 m0, s26
	s_nop 0
	global_load_lds_dwordx4 v[134:135], off
	v_lshl_add_u64 v[134:135], vcc, 0, v[160:161]
	s_add_i32 m0, s26, 0x2000
	s_nop 0
	global_load_lds_dwordx4 v[134:135], off
	s_waitcnt vmcnt(6)
	s_barrier
	s_setprio 1
	v_mfma_f32_16x16x32_bf16 v[54:57], v[214:217], v[174:177], v[54:57]
	v_mfma_f32_16x16x32_bf16 v[50:53], v[222:225], v[174:177], v[50:53]
	v_mfma_f32_16x16x32_bf16 v[38:41], v[214:217], v[190:193], v[38:41]
	v_mfma_f32_16x16x32_bf16 v[34:37], v[222:225], v[190:193], v[34:37]
	v_mfma_f32_16x16x32_bf16 v[22:25], v[214:217], v[198:201], v[22:25]
	v_mfma_f32_16x16x32_bf16 v[18:21], v[222:225], v[198:201], v[18:21]
	v_mfma_f32_16x16x32_bf16 v[6:9], v[214:217], v[206:209], v[6:9]
	v_mfma_f32_16x16x32_bf16 v[2:5], v[222:225], v[206:209], v[2:5]
	v_mfma_f32_16x16x32_bf16 v[54:57], v[218:221], v[186:189], v[54:57]
	v_mfma_f32_16x16x32_bf16 v[50:53], v[226:229], v[186:189], v[50:53]
	v_mfma_f32_16x16x32_bf16 v[38:41], v[218:221], v[194:197], v[38:41]
	v_mfma_f32_16x16x32_bf16 v[34:37], v[226:229], v[194:197], v[34:37]
	v_mfma_f32_16x16x32_bf16 v[22:25], v[218:221], v[202:205], v[22:25]
	v_mfma_f32_16x16x32_bf16 v[18:21], v[226:229], v[202:205], v[18:21]
	v_mfma_f32_16x16x32_bf16 v[6:9], v[218:221], v[210:213], v[6:9]
	v_mfma_f32_16x16x32_bf16 v[2:5], v[226:229], v[210:213], v[2:5]
	s_setprio 0
	s_add_i32 s26, 16, 0x18000
	v_add_u32_e32 v151, s26, v148
	s_barrier
	ds_read_b128 v[134:137], v151
	ds_read_b128 v[162:165], v151 offset:1024
	ds_read_b128 v[166:169], v151 offset:2048
	ds_read_b128 v[170:173], v151 offset:3072
	s_add_u32 s12, s12, 0x80000
	s_addc_u32 s13, s13, 0
	s_mov_b32 m0, s19
	v_lshl_add_u64 v[214:215], s[12:13], 0, v[154:155]
	ds_read_b128 v[174:177], v150 offset:32768
	ds_read_b128 v[186:189], v150 offset:33792
	ds_read_b128 v[190:193], v150 offset:34816
	ds_read_b128 v[194:197], v150 offset:35840
	ds_read_b128 v[198:201], v150 offset:36864
	ds_read_b128 v[202:205], v150 offset:37888
	ds_read_b128 v[206:209], v150 offset:38912
	ds_read_b128 v[210:213], v150 offset:39936
	global_load_lds_dwordx4 v[214:215], off
	v_lshl_add_u64 v[214:215], s[12:13], 0, v[158:159]
	s_mov_b32 m0, s29
	s_nop 0
	global_load_lds_dwordx4 v[214:215], off
	s_waitcnt lgkmcnt(8)
	s_barrier
	s_waitcnt lgkmcnt(0)
	s_setprio 1
	s_waitcnt lgkmcnt(0)
	v_mfma_f32_16x16x32_bf16 v[126:129], v[134:137], v[174:177], v[126:129]
	v_mfma_f32_16x16x32_bf16 v[122:125], v[166:169], v[174:177], v[122:125]
	v_mfma_f32_16x16x32_bf16 v[110:113], v[134:137], v[190:193], v[110:113]
	v_mfma_f32_16x16x32_bf16 v[106:109], v[166:169], v[190:193], v[106:109]
	v_mfma_f32_16x16x32_bf16 v[94:97], v[134:137], v[198:201], v[94:97]
	v_mfma_f32_16x16x32_bf16 v[90:93], v[166:169], v[198:201], v[90:93]
	v_mfma_f32_16x16x32_bf16 v[78:81], v[134:137], v[206:209], v[78:81]
	v_mfma_f32_16x16x32_bf16 v[74:77], v[166:169], v[206:209], v[74:77]
	v_mfma_f32_16x16x32_bf16 v[126:129], v[162:165], v[186:189], v[126:129]
	v_mfma_f32_16x16x32_bf16 v[122:125], v[170:173], v[186:189], v[122:125]
	v_mfma_f32_16x16x32_bf16 v[110:113], v[162:165], v[194:197], v[110:113]
	v_mfma_f32_16x16x32_bf16 v[106:109], v[170:173], v[194:197], v[106:109]
	v_mfma_f32_16x16x32_bf16 v[94:97], v[162:165], v[202:205], v[94:97]
	v_mfma_f32_16x16x32_bf16 v[90:93], v[170:173], v[202:205], v[90:93]
	v_mfma_f32_16x16x32_bf16 v[78:81], v[162:165], v[210:213], v[78:81]
	v_mfma_f32_16x16x32_bf16 v[74:77], v[170:173], v[210:213], v[74:77]
	s_setprio 0
	s_barrier
	s_add_i32 s12, 16, 0x1c000
	s_add_i32 s13, s26, s18
	v_add_u32_e32 v151, s12, v148
	v_lshl_add_u64 v[152:153], v[152:153], 0, s[92:93]
	s_mov_b32 m0, s13
	ds_read_b128 v[214:217], v151
	ds_read_b128 v[218:221], v151 offset:1024
	ds_read_b128 v[222:225], v151 offset:2048
	ds_read_b128 v[226:229], v151 offset:3072
	global_load_lds_dwordx4 v[152:153], off
	v_lshl_add_u64 v[152:153], v[178:179], 0, s[92:93]
	s_add_i32 m0, s13, 0x2000
	s_nop 0
	global_load_lds_dwordx4 v[152:153], off
	s_barrier
	s_waitcnt lgkmcnt(0)
	s_setprio 1
	s_waitcnt lgkmcnt(0)
	v_mfma_f32_16x16x32_bf16 v[118:121], v[214:217], v[174:177], v[118:121]
	v_mfma_f32_16x16x32_bf16 v[114:117], v[222:225], v[174:177], v[114:117]
	v_mfma_f32_16x16x32_bf16 v[102:105], v[214:217], v[190:193], v[102:105]
	v_mfma_f32_16x16x32_bf16 v[98:101], v[222:225], v[190:193], v[98:101]
	v_mfma_f32_16x16x32_bf16 v[86:89], v[214:217], v[198:201], v[86:89]
	v_mfma_f32_16x16x32_bf16 v[82:85], v[222:225], v[198:201], v[82:85]
	v_mfma_f32_16x16x32_bf16 v[70:73], v[214:217], v[206:209], v[70:73]
	v_mfma_f32_16x16x32_bf16 v[66:69], v[222:225], v[206:209], v[66:69]
	v_mfma_f32_16x16x32_bf16 v[118:121], v[218:221], v[186:189], v[118:121]
	v_mfma_f32_16x16x32_bf16 v[114:117], v[226:229], v[186:189], v[114:117]
	v_mfma_f32_16x16x32_bf16 v[102:105], v[218:221], v[194:197], v[102:105]
	v_mfma_f32_16x16x32_bf16 v[98:101], v[226:229], v[194:197], v[98:101]
	v_mfma_f32_16x16x32_bf16 v[86:89], v[218:221], v[202:205], v[86:89]
	v_mfma_f32_16x16x32_bf16 v[82:85], v[226:229], v[202:205], v[82:85]
	v_mfma_f32_16x16x32_bf16 v[70:73], v[218:221], v[210:213], v[70:73]
	v_mfma_f32_16x16x32_bf16 v[66:69], v[226:229], v[210:213], v[66:69]
	s_setprio 0
	s_mov_b32 m0, s28
	v_lshl_add_u64 v[152:153], v[230:231], 0, s[92:93]
	s_barrier
	ds_read_b128 v[174:177], v150 offset:49152
	ds_read_b128 v[186:189], v150 offset:50176
	ds_read_b128 v[190:193], v150 offset:51200
	ds_read_b128 v[194:197], v150 offset:52224
	ds_read_b128 v[198:201], v150 offset:53248
	ds_read_b128 v[202:205], v150 offset:54272
	ds_read_b128 v[206:209], v150 offset:55296
	ds_read_b128 v[210:213], v150 offset:56320
	global_load_lds_dwordx4 v[152:153], off
	v_lshl_add_u64 v[152:153], v[242:243], 0, s[92:93]
	s_mov_b32 m0, s88
	s_nop 0
	global_load_lds_dwordx4 v[152:153], off
	s_barrier
	s_waitcnt lgkmcnt(0)
	s_setprio 1
	s_waitcnt lgkmcnt(0)
	v_mfma_f32_16x16x32_bf16 v[62:65], v[134:137], v[174:177], v[62:65]
	v_mfma_f32_16x16x32_bf16 v[58:61], v[166:169], v[174:177], v[58:61]
	v_mfma_f32_16x16x32_bf16 v[46:49], v[134:137], v[190:193], v[46:49]
	v_mfma_f32_16x16x32_bf16 v[42:45], v[166:169], v[190:193], v[42:45]
	v_mfma_f32_16x16x32_bf16 v[30:33], v[134:137], v[198:201], v[30:33]
	v_mfma_f32_16x16x32_bf16 v[26:29], v[166:169], v[198:201], v[26:29]
	v_mfma_f32_16x16x32_bf16 v[14:17], v[134:137], v[206:209], v[14:17]
	v_mfma_f32_16x16x32_bf16 v[10:13], v[166:169], v[206:209], v[10:13]
	v_mfma_f32_16x16x32_bf16 v[62:65], v[162:165], v[186:189], v[62:65]
	v_mfma_f32_16x16x32_bf16 v[58:61], v[170:173], v[186:189], v[58:61]
	v_mfma_f32_16x16x32_bf16 v[46:49], v[162:165], v[194:197], v[46:49]
	v_mfma_f32_16x16x32_bf16 v[42:45], v[170:173], v[194:197], v[42:45]
	v_mfma_f32_16x16x32_bf16 v[30:33], v[162:165], v[202:205], v[30:33]
	v_mfma_f32_16x16x32_bf16 v[26:29], v[170:173], v[202:205], v[26:29]
	v_mfma_f32_16x16x32_bf16 v[14:17], v[162:165], v[210:213], v[14:17]
	v_mfma_f32_16x16x32_bf16 v[10:13], v[170:173], v[210:213], v[10:13]
	s_setprio 0
	s_barrier
	s_add_u32 s4, s4, 0x80080
	s_addc_u32 s5, s5, 0
	s_add_i32 s12, s12, s18
	v_lshl_add_u64 v[134:135], s[4:5], 0, v[156:157]
	s_mov_b32 m0, s12
	s_nop 0
	global_load_lds_dwordx4 v[134:135], off
	v_lshl_add_u64 v[134:135], s[4:5], 0, v[160:161]
	s_add_i32 m0, s12, 0x2000
	s_nop 0
	global_load_lds_dwordx4 v[134:135], off
	s_waitcnt vmcnt(6)
	s_barrier
	s_setprio 1
	v_mfma_f32_16x16x32_bf16 v[54:57], v[214:217], v[174:177], v[54:57]
	v_mfma_f32_16x16x32_bf16 v[50:53], v[222:225], v[174:177], v[50:53]
	v_mfma_f32_16x16x32_bf16 v[38:41], v[214:217], v[190:193], v[38:41]
	v_mfma_f32_16x16x32_bf16 v[34:37], v[222:225], v[190:193], v[34:37]
	v_mfma_f32_16x16x32_bf16 v[22:25], v[214:217], v[198:201], v[22:25]
	v_mfma_f32_16x16x32_bf16 v[18:21], v[222:225], v[198:201], v[18:21]
	v_mfma_f32_16x16x32_bf16 v[6:9], v[214:217], v[206:209], v[6:9]
	v_mfma_f32_16x16x32_bf16 v[2:5], v[222:225], v[206:209], v[2:5]
	v_mfma_f32_16x16x32_bf16 v[54:57], v[218:221], v[186:189], v[54:57]
	v_mfma_f32_16x16x32_bf16 v[50:53], v[226:229], v[186:189], v[50:53]
	v_mfma_f32_16x16x32_bf16 v[38:41], v[218:221], v[194:197], v[38:41]
	v_mfma_f32_16x16x32_bf16 v[34:37], v[226:229], v[194:197], v[34:37]
	v_mfma_f32_16x16x32_bf16 v[22:25], v[218:221], v[202:205], v[22:25]
	v_mfma_f32_16x16x32_bf16 v[18:21], v[226:229], v[202:205], v[18:21]
	v_mfma_f32_16x16x32_bf16 v[6:9], v[218:221], v[210:213], v[6:9]
	v_mfma_f32_16x16x32_bf16 v[2:5], v[226:229], v[210:213], v[2:5]
	s_setprio 0
	s_add_i32 s45, s45, 2
	s_add_u32 s0, s0, 0x100
	s_addc_u32 s1, s1, 0
	s_add_u32 s30, s30, 0x100
	s_addc_u32 s43, s43, 0
	s_cmp_gt_u32 s45, 29
	s_barrier
	s_cbranch_scc0 .LBB0_83
	v_lshl_add_u32 v134, s42, 8, v147
	v_ashrrev_i32_e32 v135, 31, v134
	v_readlane_b32 s4, v252, 24
	v_lshlrev_b64 v[162:163], 5, v[134:135]
	v_readlane_b32 s5, v252, 25
	v_lshlrev_b64 v[152:153], 12, v[134:135]
	s_mov_b32 s11, 0xf800000
	v_lshl_add_u64 v[166:167], s[4:5], 0, v[162:163]
	global_load_dwordx4 v[162:165], v[166:167], off
	s_nop 0
	global_load_dwordx4 v[166:169], v[166:167], off offset:16
	v_or_b32_e32 v176, 16, v134
	v_ashrrev_i32_e32 v177, 31, v176
	v_lshlrev_b64 v[176:177], 5, v[176:177]
	v_lshl_add_u64 v[176:177], s[4:5], 0, v[176:177]
	global_load_dwordx4 v[186:189], v[176:177], off
	global_load_dwordx4 v[190:193], v[176:177], off offset:16
	v_or_b32_e32 v176, 32, v134
	v_ashrrev_i32_e32 v177, 31, v176
	v_lshlrev_b64 v[176:177], 5, v[176:177]
	v_lshl_add_u64 v[176:177], s[4:5], 0, v[176:177]
	global_load_dwordx4 v[194:197], v[176:177], off
	global_load_dwordx4 v[198:201], v[176:177], off offset:16
	v_or_b32_e32 v176, 48, v134
	v_ashrrev_i32_e32 v177, 31, v176
	v_lshlrev_b64 v[176:177], 5, v[176:177]
	v_lshl_add_u64 v[176:177], s[4:5], 0, v[176:177]
	global_load_dwordx4 v[202:205], v[176:177], off
	global_load_dwordx4 v[206:209], v[176:177], off offset:16
	v_add_u32_e32 v176, 0x80, v134
	v_ashrrev_i32_e32 v177, 31, v176
	v_lshlrev_b64 v[176:177], 5, v[176:177]
	v_lshl_add_u64 v[176:177], s[4:5], 0, v[176:177]
	global_load_dwordx4 v[210:213], v[176:177], off
	global_load_dwordx4 v[214:217], v[176:177], off offset:16
	v_add_u32_e32 v176, 0x90, v134
	v_ashrrev_i32_e32 v177, 31, v176
	v_lshlrev_b64 v[176:177], 5, v[176:177]
	v_lshl_add_u64 v[176:177], s[4:5], 0, v[176:177]
	global_load_dwordx4 v[218:221], v[176:177], off
	global_load_dwordx4 v[222:225], v[176:177], off offset:16
	v_add_u32_e32 v176, 0xa0, v134
	v_ashrrev_i32_e32 v177, 31, v176
	v_lshlrev_b64 v[176:177], 5, v[176:177]
	v_lshl_add_u64 v[176:177], s[4:5], 0, v[176:177]
	global_load_dwordx4 v[226:229], v[176:177], off
	global_load_dwordx4 v[172:175], v[176:177], off offset:16
	v_lshl_or_b32 v136, s2, 8, v149
	v_readlane_b32 s2, v252, 14
	v_ashrrev_i32_e32 v137, 31, v136
	v_readlane_b32 s3, v252, 15
	v_lshlrev_b64 v[136:137], 1, v[136:137]
	s_mov_b64 s[12:13], s[24:25]
	v_lshl_add_u64 v[152:153], s[2:3], 0, v[152:153]
	v_lshl_add_u64 v[152:153], v[152:153], 0, v[136:137]
	s_mov_b32 s16, 0x1a000
	s_waitcnt vmcnt(0)
	v_mov_b32_e32 v170, v162
	v_mov_b32_e32 v171, v166
	v_mov_b32_e32 v166, v163
	v_pk_add_f32 v[162:163], v[170:171], v[166:167]
	v_mov_b32_e32 v166, v164
	v_mov_b32_e32 v167, v168
	v_mov_b32_e32 v168, v165
	v_pk_add_f32 v[164:165], v[166:167], v[168:169]
	s_nop 0
	v_pk_add_f32 v[162:163], v[162:163], v[164:165]
	s_nop 0
	v_add_f32_e32 v135, v162, v163
	v_fmamk_f32 v135, v135, 0x3a000000, v233
	v_cmp_gt_f32_e32 vcc, s11, v135
	v_mul_f32_e32 v151, 0x4f800000, v135
	s_nop 0
	v_cndmask_b32_e32 v135, v135, v151, vcc
	v_sqrt_f32_e32 v151, v135
	s_nop 0
	v_add_u32_e32 v162, -1, v151
	v_fma_f32 v163, -v162, v151, v135
	v_cmp_ge_f32_e64 s[42:43], 0, v163
	v_add_u32_e32 v163, 1, v151
	s_nop 0
	v_cndmask_b32_e64 v162, v151, v162, s[42:43]
	v_fma_f32 v151, -v163, v151, v135
	v_cmp_lt_f32_e64 s[42:43], 0, v151
	s_nop 1
	v_cndmask_b32_e64 v151, v162, v163, s[42:43]
	v_mul_f32_e32 v162, 0x37800000, v151
	v_cndmask_b32_e32 v151, v151, v162, vcc
	v_cmp_class_f32_e32 vcc, v135, v234
	s_nop 1
	v_cndmask_b32_e32 v135, v151, v135, vcc
	v_div_scale_f32 v151, s[0:1], v135, v135, 1.0
	v_rcp_f32_e32 v162, v151
	s_nop 0
	v_fma_f32 v163, -v151, v162, 1.0
	v_fmac_f32_e32 v162, v163, v162
	v_div_scale_f32 v163, vcc, 1.0, v135, 1.0
	v_mul_f32_e32 v164, v163, v162
	v_fma_f32 v165, -v151, v164, v163
	v_fmac_f32_e32 v164, v165, v162
	v_fma_f32 v151, -v151, v164, v163
	v_div_fmas_f32 v151, v151, v162, v164
	v_div_fixup_f32 v162, v151, v135, 1.0
	v_pk_mul_f32 v[128:129], v[128:129], v[162:163] op_sel_hi:[1,0]
	v_pk_mul_f32 v[126:127], v[126:127], v[162:163] op_sel_hi:[1,0]
	v_pk_mul_f32 v[164:165], v[124:125], v[162:163] op_sel_hi:[1,0]
	v_pk_mul_f32 v[124:125], v[122:123], v[162:163] op_sel_hi:[1,0]
	v_cvt_pk_bf16_f32 v122, v126, v127
	v_cvt_pk_bf16_f32 v123, v128, v129
	v_cvt_pk_bf16_f32 v124, v124, v125
	v_cvt_pk_bf16_f32 v125, v164, v165
	global_store_dwordx4 v[152:153], v[122:125], off
	v_pk_mul_f32 v[120:121], v[120:121], v[162:163] op_sel_hi:[1,0]
	v_pk_mul_f32 v[118:119], v[118:119], v[162:163] op_sel_hi:[1,0]
	v_pk_mul_f32 v[122:123], v[116:117], v[162:163] op_sel_hi:[1,0]
	v_pk_mul_f32 v[116:117], v[114:115], v[162:163] op_sel_hi:[1,0]
	v_cvt_pk_bf16_f32 v114, v118, v119
	v_cvt_pk_bf16_f32 v115, v120, v121
	v_cvt_pk_bf16_f32 v116, v116, v117
	v_cvt_pk_bf16_f32 v117, v122, v123
	global_store_dwordx4 v[152:153], v[114:117], off offset:256
	s_nop 1
	v_or_b32_e32 v116, 16, v134
	v_ashrrev_i32_e32 v117, 31, v116
	v_lshlrev_b64 v[114:115], 12, v[116:117]
	v_lshlrev_b64 v[116:117], 5, v[116:117]
	v_lshl_add_u64 v[120:121], s[4:5], 0, v[116:117]
	s_nop 0
	v_lshl_add_u64 v[114:115], s[2:3], 0, v[114:115]
	v_lshl_add_u64 v[114:115], v[114:115], 0, v[136:137]
	v_mov_b32_e32 v116, v186
	v_mov_b32_e32 v117, v187
	v_mov_b32_e32 v118, v188
	v_mov_b32_e32 v119, v189
	v_mov_b32_e32 v120, v190
	v_mov_b32_e32 v121, v191
	v_mov_b32_e32 v122, v192
	v_mov_b32_e32 v123, v193
	v_mov_b32_e32 v124, v116
	v_mov_b32_e32 v125, v120
	v_mov_b32_e32 v120, v117
	v_pk_add_f32 v[116:117], v[124:125], v[120:121]
	v_mov_b32_e32 v120, v118
	v_mov_b32_e32 v121, v122
	v_mov_b32_e32 v122, v119
	v_pk_add_f32 v[118:119], v[120:121], v[122:123]
	s_nop 0
	v_pk_add_f32 v[116:117], v[116:117], v[118:119]
	s_nop 0
	v_add_f32_e32 v116, v116, v117
	v_fmamk_f32 v116, v116, 0x3a000000, v233
	v_cmp_gt_f32_e32 vcc, s11, v116
	v_mul_f32_e32 v117, 0x4f800000, v116
	s_nop 0
	v_cndmask_b32_e32 v116, v116, v117, vcc
	v_sqrt_f32_e32 v117, v116
	s_nop 0
	v_add_u32_e32 v118, -1, v117
	v_fma_f32 v119, -v118, v117, v116
	v_cmp_ge_f32_e64 s[42:43], 0, v119
	v_add_u32_e32 v119, 1, v117
	s_nop 0
	v_cndmask_b32_e64 v118, v117, v118, s[42:43]
	v_fma_f32 v117, -v119, v117, v116
	v_cmp_lt_f32_e64 s[42:43], 0, v117
	s_nop 1
	v_cndmask_b32_e64 v117, v118, v119, s[42:43]
	v_mul_f32_e32 v118, 0x37800000, v117
	v_cndmask_b32_e32 v117, v117, v118, vcc
	v_cmp_class_f32_e32 vcc, v116, v234
	s_nop 1
	v_cndmask_b32_e32 v116, v117, v116, vcc
	v_div_scale_f32 v117, s[0:1], v116, v116, 1.0
	v_rcp_f32_e32 v118, v117
	s_nop 0
	v_fma_f32 v119, -v117, v118, 1.0
	v_fmac_f32_e32 v118, v119, v118
	v_div_scale_f32 v119, vcc, 1.0, v116, 1.0
	v_mul_f32_e32 v120, v119, v118
	v_fma_f32 v121, -v117, v120, v119
	v_fmac_f32_e32 v120, v121, v118
	v_fma_f32 v117, -v117, v120, v119
	v_div_fmas_f32 v117, v117, v118, v120
	v_div_fixup_f32 v116, v117, v116, 1.0
	v_pk_mul_f32 v[112:113], v[112:113], v[116:117] op_sel_hi:[1,0]
	v_pk_mul_f32 v[110:111], v[110:111], v[116:117] op_sel_hi:[1,0]
	v_pk_mul_f32 v[118:119], v[108:109], v[116:117] op_sel_hi:[1,0]
	v_pk_mul_f32 v[108:109], v[106:107], v[116:117] op_sel_hi:[1,0]
	v_cvt_pk_bf16_f32 v106, v110, v111
	v_cvt_pk_bf16_f32 v107, v112, v113
	v_cvt_pk_bf16_f32 v108, v108, v109
	v_cvt_pk_bf16_f32 v109, v118, v119
	global_store_dwordx4 v[114:115], v[106:109], off
	v_pk_mul_f32 v[104:105], v[104:105], v[116:117] op_sel_hi:[1,0]
	v_pk_mul_f32 v[102:103], v[102:103], v[116:117] op_sel_hi:[1,0]
	v_pk_mul_f32 v[106:107], v[100:101], v[116:117] op_sel_hi:[1,0]
	v_pk_mul_f32 v[100:101], v[98:99], v[116:117] op_sel_hi:[1,0]
	v_cvt_pk_bf16_f32 v98, v102, v103
	v_cvt_pk_bf16_f32 v99, v104, v105
	v_cvt_pk_bf16_f32 v100, v100, v101
	v_cvt_pk_bf16_f32 v101, v106, v107
	global_store_dwordx4 v[114:115], v[98:101], off offset:256
	s_nop 1
	v_or_b32_e32 v100, 32, v134
	v_ashrrev_i32_e32 v101, 31, v100
	v_lshlrev_b64 v[98:99], 12, v[100:101]
	v_lshlrev_b64 v[100:101], 5, v[100:101]
	v_lshl_add_u64 v[104:105], s[4:5], 0, v[100:101]
	s_nop 0
	v_lshl_add_u64 v[98:99], s[2:3], 0, v[98:99]
	v_lshl_add_u64 v[98:99], v[98:99], 0, v[136:137]
	v_mov_b32_e32 v100, v194
	v_mov_b32_e32 v101, v195
	v_mov_b32_e32 v102, v196
	v_mov_b32_e32 v103, v197
	v_mov_b32_e32 v104, v198
	v_mov_b32_e32 v105, v199
	v_mov_b32_e32 v106, v200
	v_mov_b32_e32 v107, v201
	v_mov_b32_e32 v108, v100
	v_mov_b32_e32 v109, v104
	v_mov_b32_e32 v104, v101
	v_pk_add_f32 v[100:101], v[108:109], v[104:105]
	v_mov_b32_e32 v104, v102
	v_mov_b32_e32 v105, v106
	v_mov_b32_e32 v106, v103
	v_pk_add_f32 v[102:103], v[104:105], v[106:107]
	s_nop 0
	v_pk_add_f32 v[100:101], v[100:101], v[102:103]
	s_nop 0
	v_add_f32_e32 v100, v100, v101
	v_fmamk_f32 v100, v100, 0x3a000000, v233
	v_cmp_gt_f32_e32 vcc, s11, v100
	v_mul_f32_e32 v101, 0x4f800000, v100
	s_nop 0
	v_cndmask_b32_e32 v100, v100, v101, vcc
	v_sqrt_f32_e32 v101, v100
	s_nop 0
	v_add_u32_e32 v102, -1, v101
	v_fma_f32 v103, -v102, v101, v100
	v_cmp_ge_f32_e64 s[42:43], 0, v103
	v_add_u32_e32 v103, 1, v101
	s_nop 0
	v_cndmask_b32_e64 v102, v101, v102, s[42:43]
	v_fma_f32 v101, -v103, v101, v100
	v_cmp_lt_f32_e64 s[42:43], 0, v101
	s_nop 1
	v_cndmask_b32_e64 v101, v102, v103, s[42:43]
	v_mul_f32_e32 v102, 0x37800000, v101
	v_cndmask_b32_e32 v101, v101, v102, vcc
	v_cmp_class_f32_e32 vcc, v100, v234
	s_nop 1
	v_cndmask_b32_e32 v100, v101, v100, vcc
	v_div_scale_f32 v101, s[0:1], v100, v100, 1.0
	v_rcp_f32_e32 v102, v101
	s_nop 0
	v_fma_f32 v103, -v101, v102, 1.0
	v_fmac_f32_e32 v102, v103, v102
	v_div_scale_f32 v103, vcc, 1.0, v100, 1.0
	v_mul_f32_e32 v104, v103, v102
	v_fma_f32 v105, -v101, v104, v103
	v_fmac_f32_e32 v104, v105, v102
	v_fma_f32 v101, -v101, v104, v103
	v_div_fmas_f32 v101, v101, v102, v104
	v_div_fixup_f32 v100, v101, v100, 1.0
	v_pk_mul_f32 v[96:97], v[96:97], v[100:101] op_sel_hi:[1,0]
	v_pk_mul_f32 v[94:95], v[94:95], v[100:101] op_sel_hi:[1,0]
	v_pk_mul_f32 v[102:103], v[92:93], v[100:101] op_sel_hi:[1,0]
	v_pk_mul_f32 v[92:93], v[90:91], v[100:101] op_sel_hi:[1,0]
	v_cvt_pk_bf16_f32 v90, v94, v95
	v_cvt_pk_bf16_f32 v91, v96, v97
	v_cvt_pk_bf16_f32 v92, v92, v93
	v_cvt_pk_bf16_f32 v93, v102, v103
	global_store_dwordx4 v[98:99], v[90:93], off
	v_pk_mul_f32 v[88:89], v[88:89], v[100:101] op_sel_hi:[1,0]
	v_pk_mul_f32 v[86:87], v[86:87], v[100:101] op_sel_hi:[1,0]
	v_pk_mul_f32 v[90:91], v[84:85], v[100:101] op_sel_hi:[1,0]
	v_pk_mul_f32 v[84:85], v[82:83], v[100:101] op_sel_hi:[1,0]
	v_cvt_pk_bf16_f32 v82, v86, v87
	v_cvt_pk_bf16_f32 v83, v88, v89
	v_cvt_pk_bf16_f32 v84, v84, v85
	v_cvt_pk_bf16_f32 v85, v90, v91
	global_store_dwordx4 v[98:99], v[82:85], off offset:256
	s_nop 1
	v_or_b32_e32 v84, 48, v134
	v_ashrrev_i32_e32 v85, 31, v84
	v_lshlrev_b64 v[82:83], 12, v[84:85]
	v_lshlrev_b64 v[84:85], 5, v[84:85]
	v_lshl_add_u64 v[88:89], s[4:5], 0, v[84:85]
	s_nop 0
	v_lshl_add_u64 v[82:83], s[2:3], 0, v[82:83]
	v_lshl_add_u64 v[82:83], v[82:83], 0, v[136:137]
	v_mov_b32_e32 v84, v202
	v_mov_b32_e32 v85, v203
	v_mov_b32_e32 v86, v204
	v_mov_b32_e32 v87, v205
	v_mov_b32_e32 v88, v206
	v_mov_b32_e32 v89, v207
	v_mov_b32_e32 v90, v208
	v_mov_b32_e32 v91, v209
	v_mov_b32_e32 v92, v84
	v_mov_b32_e32 v93, v88
	v_mov_b32_e32 v88, v85
	v_pk_add_f32 v[84:85], v[92:93], v[88:89]
	v_mov_b32_e32 v88, v86
	v_mov_b32_e32 v89, v90
	v_mov_b32_e32 v90, v87
	v_pk_add_f32 v[86:87], v[88:89], v[90:91]
	s_nop 0
	v_pk_add_f32 v[84:85], v[84:85], v[86:87]
	s_nop 0
	v_add_f32_e32 v84, v84, v85
	v_fmamk_f32 v84, v84, 0x3a000000, v233
	v_cmp_gt_f32_e32 vcc, s11, v84
	v_mul_f32_e32 v85, 0x4f800000, v84
	s_nop 0
	v_cndmask_b32_e32 v84, v84, v85, vcc
	v_sqrt_f32_e32 v85, v84
	s_nop 0
	v_add_u32_e32 v86, -1, v85
	v_fma_f32 v87, -v86, v85, v84
	v_cmp_ge_f32_e64 s[42:43], 0, v87
	v_add_u32_e32 v87, 1, v85
	s_nop 0
	v_cndmask_b32_e64 v86, v85, v86, s[42:43]
	v_fma_f32 v85, -v87, v85, v84
	v_cmp_lt_f32_e64 s[42:43], 0, v85
	s_nop 1
	v_cndmask_b32_e64 v85, v86, v87, s[42:43]
	v_mul_f32_e32 v86, 0x37800000, v85
	v_cndmask_b32_e32 v85, v85, v86, vcc
	v_cmp_class_f32_e32 vcc, v84, v234
	s_nop 1
	v_cndmask_b32_e32 v84, v85, v84, vcc
	v_div_scale_f32 v85, s[0:1], v84, v84, 1.0
	v_rcp_f32_e32 v86, v85
	s_nop 0
	v_fma_f32 v87, -v85, v86, 1.0
	v_fmac_f32_e32 v86, v87, v86
	v_div_scale_f32 v87, vcc, 1.0, v84, 1.0
	v_mul_f32_e32 v88, v87, v86
	v_fma_f32 v89, -v85, v88, v87
	v_fmac_f32_e32 v88, v89, v86
	v_fma_f32 v85, -v85, v88, v87
	v_div_fmas_f32 v85, v85, v86, v88
	v_div_fixup_f32 v84, v85, v84, 1.0
	v_pk_mul_f32 v[80:81], v[80:81], v[84:85] op_sel_hi:[1,0]
	v_pk_mul_f32 v[78:79], v[78:79], v[84:85] op_sel_hi:[1,0]
	v_pk_mul_f32 v[86:87], v[76:77], v[84:85] op_sel_hi:[1,0]
	v_pk_mul_f32 v[76:77], v[74:75], v[84:85] op_sel_hi:[1,0]
	v_cvt_pk_bf16_f32 v74, v78, v79
	v_cvt_pk_bf16_f32 v75, v80, v81
	v_cvt_pk_bf16_f32 v76, v76, v77
	v_cvt_pk_bf16_f32 v77, v86, v87
	global_store_dwordx4 v[82:83], v[74:77], off
	v_pk_mul_f32 v[72:73], v[72:73], v[84:85] op_sel_hi:[1,0]
	v_pk_mul_f32 v[70:71], v[70:71], v[84:85] op_sel_hi:[1,0]
	v_pk_mul_f32 v[74:75], v[68:69], v[84:85] op_sel_hi:[1,0]
	v_pk_mul_f32 v[68:69], v[66:67], v[84:85] op_sel_hi:[1,0]
	v_cvt_pk_bf16_f32 v66, v70, v71
	v_cvt_pk_bf16_f32 v67, v72, v73
	v_cvt_pk_bf16_f32 v68, v68, v69
	v_cvt_pk_bf16_f32 v69, v74, v75
	global_store_dwordx4 v[82:83], v[66:69], off offset:256
	s_nop 1
	v_add_u32_e32 v68, 0x80, v134
	v_ashrrev_i32_e32 v69, 31, v68
	v_lshlrev_b64 v[66:67], 12, v[68:69]
	v_lshlrev_b64 v[68:69], 5, v[68:69]
	v_lshl_add_u64 v[72:73], s[4:5], 0, v[68:69]
	s_nop 0
	v_lshl_add_u64 v[66:67], s[2:3], 0, v[66:67]
	v_lshl_add_u64 v[66:67], v[66:67], 0, v[136:137]
	v_mov_b32_e32 v68, v210
	v_mov_b32_e32 v69, v211
	v_mov_b32_e32 v70, v212
	v_mov_b32_e32 v71, v213
	v_mov_b32_e32 v72, v214
	v_mov_b32_e32 v73, v215
	v_mov_b32_e32 v74, v216
	v_mov_b32_e32 v75, v217
	v_mov_b32_e32 v76, v68
	v_mov_b32_e32 v77, v72
	v_mov_b32_e32 v72, v69
	v_pk_add_f32 v[68:69], v[76:77], v[72:73]
	v_mov_b32_e32 v72, v70
	v_mov_b32_e32 v73, v74
	v_mov_b32_e32 v74, v71
	v_pk_add_f32 v[70:71], v[72:73], v[74:75]
	s_nop 0
	v_pk_add_f32 v[68:69], v[68:69], v[70:71]
	s_nop 0
	v_add_f32_e32 v68, v68, v69
	v_fmamk_f32 v68, v68, 0x3a000000, v233
	v_cmp_gt_f32_e32 vcc, s11, v68
	v_mul_f32_e32 v69, 0x4f800000, v68
	s_nop 0
	v_cndmask_b32_e32 v68, v68, v69, vcc
	v_sqrt_f32_e32 v69, v68
	s_nop 0
	v_add_u32_e32 v70, -1, v69
	v_fma_f32 v71, -v70, v69, v68
	v_cmp_ge_f32_e64 s[42:43], 0, v71
	v_add_u32_e32 v71, 1, v69
	s_nop 0
	v_cndmask_b32_e64 v70, v69, v70, s[42:43]
	v_fma_f32 v69, -v71, v69, v68
	v_cmp_lt_f32_e64 s[42:43], 0, v69
	s_nop 1
	v_cndmask_b32_e64 v69, v70, v71, s[42:43]
	v_mul_f32_e32 v70, 0x37800000, v69
	v_cndmask_b32_e32 v69, v69, v70, vcc
	v_cmp_class_f32_e32 vcc, v68, v234
	s_nop 1
	v_cndmask_b32_e32 v68, v69, v68, vcc
	v_div_scale_f32 v69, s[0:1], v68, v68, 1.0
	v_rcp_f32_e32 v70, v69
	s_nop 0
	v_fma_f32 v71, -v69, v70, 1.0
	v_fmac_f32_e32 v70, v71, v70
	v_div_scale_f32 v71, vcc, 1.0, v68, 1.0
	v_mul_f32_e32 v72, v71, v70
	v_fma_f32 v73, -v69, v72, v71
	v_fmac_f32_e32 v72, v73, v70
	v_fma_f32 v69, -v69, v72, v71
	v_div_fmas_f32 v69, v69, v70, v72
	v_div_fixup_f32 v68, v69, v68, 1.0
	v_pk_mul_f32 v[64:65], v[64:65], v[68:69] op_sel_hi:[1,0]
	v_pk_mul_f32 v[62:63], v[62:63], v[68:69] op_sel_hi:[1,0]
	v_pk_mul_f32 v[70:71], v[60:61], v[68:69] op_sel_hi:[1,0]
	v_pk_mul_f32 v[60:61], v[58:59], v[68:69] op_sel_hi:[1,0]
	v_cvt_pk_bf16_f32 v58, v62, v63
	v_cvt_pk_bf16_f32 v59, v64, v65
	v_cvt_pk_bf16_f32 v60, v60, v61
	v_cvt_pk_bf16_f32 v61, v70, v71
	global_store_dwordx4 v[66:67], v[58:61], off
	v_pk_mul_f32 v[56:57], v[56:57], v[68:69] op_sel_hi:[1,0]
	v_pk_mul_f32 v[54:55], v[54:55], v[68:69] op_sel_hi:[1,0]
	v_pk_mul_f32 v[58:59], v[52:53], v[68:69] op_sel_hi:[1,0]
	v_pk_mul_f32 v[52:53], v[50:51], v[68:69] op_sel_hi:[1,0]
	v_cvt_pk_bf16_f32 v50, v54, v55
	v_cvt_pk_bf16_f32 v51, v56, v57
	v_cvt_pk_bf16_f32 v52, v52, v53
	v_cvt_pk_bf16_f32 v53, v58, v59
	global_store_dwordx4 v[66:67], v[50:53], off offset:256
	s_nop 1
	v_add_u32_e32 v52, 0x90, v134
	v_ashrrev_i32_e32 v53, 31, v52
	v_lshlrev_b64 v[50:51], 12, v[52:53]
	v_lshlrev_b64 v[52:53], 5, v[52:53]
	v_lshl_add_u64 v[56:57], s[4:5], 0, v[52:53]
	s_nop 0
	v_lshl_add_u64 v[50:51], s[2:3], 0, v[50:51]
	v_lshl_add_u64 v[50:51], v[50:51], 0, v[136:137]
	v_mov_b32_e32 v52, v218
	v_mov_b32_e32 v53, v219
	v_mov_b32_e32 v54, v220
	v_mov_b32_e32 v55, v221
	v_mov_b32_e32 v56, v222
	v_mov_b32_e32 v57, v223
	v_mov_b32_e32 v58, v224
	v_mov_b32_e32 v59, v225
	v_mov_b32_e32 v60, v52
	v_mov_b32_e32 v61, v56
	v_mov_b32_e32 v56, v53
	v_pk_add_f32 v[52:53], v[60:61], v[56:57]
	v_mov_b32_e32 v56, v54
	v_mov_b32_e32 v57, v58
	v_mov_b32_e32 v58, v55
	v_pk_add_f32 v[54:55], v[56:57], v[58:59]
	s_nop 0
	v_pk_add_f32 v[52:53], v[52:53], v[54:55]
	s_nop 0
	v_add_f32_e32 v52, v52, v53
	v_fmamk_f32 v52, v52, 0x3a000000, v233
	v_cmp_gt_f32_e32 vcc, s11, v52
	v_mul_f32_e32 v53, 0x4f800000, v52
	s_nop 0
	v_cndmask_b32_e32 v52, v52, v53, vcc
	v_sqrt_f32_e32 v53, v52
	s_nop 0
	v_add_u32_e32 v54, -1, v53
	v_fma_f32 v55, -v54, v53, v52
	v_cmp_ge_f32_e64 s[42:43], 0, v55
	v_add_u32_e32 v55, 1, v53
	s_nop 0
	v_cndmask_b32_e64 v54, v53, v54, s[42:43]
	v_fma_f32 v53, -v55, v53, v52
	v_cmp_lt_f32_e64 s[42:43], 0, v53
	s_nop 1
	v_cndmask_b32_e64 v53, v54, v55, s[42:43]
	v_mul_f32_e32 v54, 0x37800000, v53
	v_cndmask_b32_e32 v53, v53, v54, vcc
	v_cmp_class_f32_e32 vcc, v52, v234
	s_nop 1
	v_cndmask_b32_e32 v52, v53, v52, vcc
	v_div_scale_f32 v53, s[0:1], v52, v52, 1.0
	v_rcp_f32_e32 v54, v53
	s_nop 0
	v_fma_f32 v55, -v53, v54, 1.0
	v_fmac_f32_e32 v54, v55, v54
	v_div_scale_f32 v55, vcc, 1.0, v52, 1.0
	v_mul_f32_e32 v56, v55, v54
	v_fma_f32 v57, -v53, v56, v55
	v_fmac_f32_e32 v56, v57, v54
	v_fma_f32 v53, -v53, v56, v55
	v_div_fmas_f32 v53, v53, v54, v56
	v_div_fixup_f32 v52, v53, v52, 1.0
	v_pk_mul_f32 v[48:49], v[48:49], v[52:53] op_sel_hi:[1,0]
	v_pk_mul_f32 v[46:47], v[46:47], v[52:53] op_sel_hi:[1,0]
	v_pk_mul_f32 v[54:55], v[44:45], v[52:53] op_sel_hi:[1,0]
	v_pk_mul_f32 v[44:45], v[42:43], v[52:53] op_sel_hi:[1,0]
	v_cvt_pk_bf16_f32 v42, v46, v47
	v_cvt_pk_bf16_f32 v43, v48, v49
	v_cvt_pk_bf16_f32 v44, v44, v45
	v_cvt_pk_bf16_f32 v45, v54, v55
	global_store_dwordx4 v[50:51], v[42:45], off
	v_pk_mul_f32 v[40:41], v[40:41], v[52:53] op_sel_hi:[1,0]
	v_pk_mul_f32 v[38:39], v[38:39], v[52:53] op_sel_hi:[1,0]
	v_pk_mul_f32 v[42:43], v[36:37], v[52:53] op_sel_hi:[1,0]
	v_pk_mul_f32 v[36:37], v[34:35], v[52:53] op_sel_hi:[1,0]
	v_cvt_pk_bf16_f32 v34, v38, v39
	v_cvt_pk_bf16_f32 v35, v40, v41
	v_cvt_pk_bf16_f32 v36, v36, v37
	v_cvt_pk_bf16_f32 v37, v42, v43
	global_store_dwordx4 v[50:51], v[34:37], off offset:256
	s_nop 1
	v_add_u32_e32 v36, 0xa0, v134
	v_ashrrev_i32_e32 v37, 31, v36
	v_lshlrev_b64 v[34:35], 12, v[36:37]
	v_lshlrev_b64 v[36:37], 5, v[36:37]
	v_lshl_add_u64 v[40:41], s[4:5], 0, v[36:37]
	s_nop 0
	v_lshl_add_u64 v[34:35], s[2:3], 0, v[34:35]
	v_lshl_add_u64 v[34:35], v[34:35], 0, v[136:137]
	v_mov_b32_e32 v36, v226
	v_mov_b32_e32 v37, v227
	v_mov_b32_e32 v38, v228
	v_mov_b32_e32 v39, v229
	v_mov_b32_e32 v40, v172
	v_mov_b32_e32 v41, v173
	v_mov_b32_e32 v42, v174
	v_mov_b32_e32 v43, v175
	v_mov_b32_e32 v44, v36
	v_mov_b32_e32 v45, v40
	v_mov_b32_e32 v40, v37
	v_pk_add_f32 v[36:37], v[44:45], v[40:41]
	v_mov_b32_e32 v40, v38
	v_mov_b32_e32 v41, v42
	v_mov_b32_e32 v42, v39
	v_pk_add_f32 v[38:39], v[40:41], v[42:43]
	s_nop 0
	v_pk_add_f32 v[36:37], v[36:37], v[38:39]
	s_nop 0
	v_add_f32_e32 v36, v36, v37
	v_fmamk_f32 v36, v36, 0x3a000000, v233
	v_cmp_gt_f32_e32 vcc, s11, v36
	v_mul_f32_e32 v37, 0x4f800000, v36
	s_nop 0
	v_cndmask_b32_e32 v36, v36, v37, vcc
	v_sqrt_f32_e32 v37, v36
	s_nop 0
	v_add_u32_e32 v38, -1, v37
	v_fma_f32 v39, -v38, v37, v36
	v_cmp_ge_f32_e64 s[42:43], 0, v39
	v_add_u32_e32 v39, 1, v37
	s_nop 0
	v_cndmask_b32_e64 v38, v37, v38, s[42:43]
	v_fma_f32 v37, -v39, v37, v36
	v_cmp_lt_f32_e64 s[42:43], 0, v37
	s_nop 1
	v_cndmask_b32_e64 v37, v38, v39, s[42:43]
	v_mul_f32_e32 v38, 0x37800000, v37
	v_cndmask_b32_e32 v37, v37, v38, vcc
	v_cmp_class_f32_e32 vcc, v36, v234
	s_nop 1
	v_cndmask_b32_e32 v36, v37, v36, vcc
	v_div_scale_f32 v37, s[0:1], v36, v36, 1.0
	v_rcp_f32_e32 v38, v37
	s_nop 0
	v_fma_f32 v39, -v37, v38, 1.0
	v_fmac_f32_e32 v38, v39, v38
	v_div_scale_f32 v39, vcc, 1.0, v36, 1.0
	v_mul_f32_e32 v40, v39, v38
	v_fma_f32 v41, -v37, v40, v39
	v_fmac_f32_e32 v40, v41, v38
	v_fma_f32 v37, -v37, v40, v39
	v_div_fmas_f32 v37, v37, v38, v40
	v_div_fixup_f32 v36, v37, v36, 1.0
	v_pk_mul_f32 v[32:33], v[32:33], v[36:37] op_sel_hi:[1,0]
	v_pk_mul_f32 v[30:31], v[30:31], v[36:37] op_sel_hi:[1,0]
	v_pk_mul_f32 v[38:39], v[28:29], v[36:37] op_sel_hi:[1,0]
	v_pk_mul_f32 v[28:29], v[26:27], v[36:37] op_sel_hi:[1,0]
	v_cvt_pk_bf16_f32 v26, v30, v31
	v_cvt_pk_bf16_f32 v27, v32, v33
	v_cvt_pk_bf16_f32 v28, v28, v29
	v_cvt_pk_bf16_f32 v29, v38, v39
	global_store_dwordx4 v[34:35], v[26:29], off
	v_pk_mul_f32 v[24:25], v[24:25], v[36:37] op_sel_hi:[1,0]
	v_pk_mul_f32 v[22:23], v[22:23], v[36:37] op_sel_hi:[1,0]
	v_pk_mul_f32 v[26:27], v[20:21], v[36:37] op_sel_hi:[1,0]
	v_pk_mul_f32 v[20:21], v[18:19], v[36:37] op_sel_hi:[1,0]
	v_cvt_pk_bf16_f32 v18, v22, v23
	v_cvt_pk_bf16_f32 v19, v24, v25
	v_cvt_pk_bf16_f32 v20, v20, v21
	v_cvt_pk_bf16_f32 v21, v26, v27
	global_store_dwordx4 v[34:35], v[18:21], off offset:256
	s_nop 1
	v_add_u32_e32 v20, 0xb0, v134
	v_ashrrev_i32_e32 v21, 31, v20
	v_lshlrev_b64 v[18:19], 12, v[20:21]
	v_lshlrev_b64 v[20:21], 5, v[20:21]
	v_lshl_add_u64 v[24:25], s[4:5], 0, v[20:21]
	global_load_dwordx4 v[20:23], v[24:25], off
	s_nop 0
	global_load_dwordx4 v[24:27], v[24:25], off offset:16
	v_lshl_add_u64 v[18:19], s[2:3], 0, v[18:19]
	v_lshl_add_u64 v[18:19], v[18:19], 0, v[136:137]
	s_mov_b32 s2, s10
	s_waitcnt vmcnt(0)
	v_mov_b32_e32 v28, v20
	v_mov_b32_e32 v29, v24
	v_mov_b32_e32 v24, v21
	v_pk_add_f32 v[20:21], v[28:29], v[24:25]
	v_mov_b32_e32 v24, v22
	v_mov_b32_e32 v25, v26
	v_mov_b32_e32 v26, v23
	v_pk_add_f32 v[22:23], v[24:25], v[26:27]
	s_nop 0
	v_pk_add_f32 v[20:21], v[20:21], v[22:23]
	s_nop 0
	v_add_f32_e32 v20, v20, v21
	v_fmamk_f32 v20, v20, 0x3a000000, v233
	v_cmp_gt_f32_e32 vcc, s11, v20
	v_mul_f32_e32 v21, 0x4f800000, v20
	s_nop 0
	v_cndmask_b32_e32 v20, v20, v21, vcc
	v_sqrt_f32_e32 v21, v20
	s_nop 0
	v_add_u32_e32 v22, -1, v21
	v_fma_f32 v23, -v22, v21, v20
	v_cmp_ge_f32_e64 s[42:43], 0, v23
	v_add_u32_e32 v23, 1, v21
	s_nop 0
	v_cndmask_b32_e64 v22, v21, v22, s[42:43]
	v_fma_f32 v21, -v23, v21, v20
	v_cmp_lt_f32_e64 s[42:43], 0, v21
	s_nop 1
	v_cndmask_b32_e64 v21, v22, v23, s[42:43]
	v_mul_f32_e32 v22, 0x37800000, v21
	v_cndmask_b32_e32 v21, v21, v22, vcc
	v_cmp_class_f32_e32 vcc, v20, v234
	s_mov_b32 s42, s14
	s_nop 0
	v_cndmask_b32_e32 v20, v21, v20, vcc
	v_div_scale_f32 v21, s[0:1], v20, v20, 1.0
	v_rcp_f32_e32 v22, v21
	s_mov_b64 s[0:1], s[46:47]
	v_readlane_b32 s46, v255, 49
	v_fma_f32 v23, -v21, v22, 1.0
	v_fmac_f32_e32 v22, v23, v22
	v_div_scale_f32 v23, vcc, 1.0, v20, 1.0
	v_mul_f32_e32 v24, v23, v22
	v_fma_f32 v25, -v21, v24, v23
	v_fmac_f32_e32 v24, v25, v22
	v_fma_f32 v21, -v21, v24, v23
	v_div_fmas_f32 v21, v21, v22, v24
	v_div_fixup_f32 v20, v21, v20, 1.0
	v_pk_mul_f32 v[16:17], v[16:17], v[20:21] op_sel_hi:[1,0]
	v_pk_mul_f32 v[14:15], v[14:15], v[20:21] op_sel_hi:[1,0]
	v_pk_mul_f32 v[22:23], v[12:13], v[20:21] op_sel_hi:[1,0]
	v_pk_mul_f32 v[12:13], v[10:11], v[20:21] op_sel_hi:[1,0]
	v_cvt_pk_bf16_f32 v10, v14, v15
	v_cvt_pk_bf16_f32 v11, v16, v17
	v_cvt_pk_bf16_f32 v12, v12, v13
	v_cvt_pk_bf16_f32 v13, v22, v23
	global_store_dwordx4 v[18:19], v[10:13], off
	v_pk_mul_f32 v[8:9], v[8:9], v[20:21] op_sel_hi:[1,0]
	v_pk_mul_f32 v[6:7], v[6:7], v[20:21] op_sel_hi:[1,0]
	v_pk_mul_f32 v[10:11], v[4:5], v[20:21] op_sel_hi:[1,0]
	v_pk_mul_f32 v[4:5], v[2:3], v[20:21] op_sel_hi:[1,0]
	v_cvt_pk_bf16_f32 v2, v6, v7
	v_cvt_pk_bf16_f32 v3, v8, v9
	v_cvt_pk_bf16_f32 v4, v4, v5
	v_cvt_pk_bf16_f32 v5, v10, v11
	s_and_b64 vcc, exec, s[40:41]
	global_store_dwordx4 v[18:19], v[2:5], off offset:256
	s_cbranch_vccz .LBB0_76
	s_waitcnt vmcnt(0)
	s_cmpk_gt_u32 s55, 0xff
	s_cbranch_scc1 .LBB0_87
	s_barrier

.LBB0_104:
	s_add_u32 s4, s0, 0xfff80080
	s_addc_u32 s5, s1, -1
	s_add_i32 s26, 16, 0x10000
	v_add_u32_e32 v151, s26, v148
	ds_read_b128 v[134:137], v151
	ds_read_b128 v[162:165], v151 offset:1024
	ds_read_b128 v[166:169], v151 offset:2048
	ds_read_b128 v[170:173], v151 offset:3072
	s_cmp_eq_u32 s47, 28
	s_cselect_b32 s13, s3, s5
	s_cselect_b32 s12, s15, s4
	s_cselect_b32 s5, s11, s45
	s_cselect_b32 s4, s16, s30
	v_lshl_add_u64 v[152:153], s[0:1], 0, v[130:131]
	s_add_i32 m0, s88, 0xc000
	ds_read_b128 v[174:177], v150
	ds_read_b128 v[186:189], v150 offset:1024
	ds_read_b128 v[190:193], v150 offset:2048
	ds_read_b128 v[194:197], v150 offset:3072
	ds_read_b128 v[198:201], v150 offset:4096
	ds_read_b128 v[202:205], v150 offset:5120
	ds_read_b128 v[206:209], v150 offset:6144
	ds_read_b128 v[210:213], v150 offset:7168
	global_load_lds_dwordx4 v[152:153], off
	v_lshl_add_u64 v[152:153], s[0:1], 0, v[132:133]
	s_add_i32 m0, s88, 0xe000
	s_nop 0
	global_load_lds_dwordx4 v[152:153], off
	s_waitcnt lgkmcnt(8)
	s_barrier
	s_waitcnt lgkmcnt(0)
	s_setprio 1
	s_waitcnt lgkmcnt(0)
	v_mfma_f32_16x16x32_bf16 v[126:129], v[134:137], v[174:177], v[126:129]
	v_mfma_f32_16x16x32_bf16 v[122:125], v[166:169], v[174:177], v[122:125]
	v_mfma_f32_16x16x32_bf16 v[110:113], v[134:137], v[190:193], v[110:113]
	v_mfma_f32_16x16x32_bf16 v[106:109], v[166:169], v[190:193], v[106:109]
	v_mfma_f32_16x16x32_bf16 v[94:97], v[134:137], v[198:201], v[94:97]
	v_mfma_f32_16x16x32_bf16 v[90:93], v[166:169], v[198:201], v[90:93]
	v_mfma_f32_16x16x32_bf16 v[78:81], v[134:137], v[206:209], v[78:81]
	v_mfma_f32_16x16x32_bf16 v[74:77], v[166:169], v[206:209], v[74:77]
	v_mfma_f32_16x16x32_bf16 v[126:129], v[162:165], v[186:189], v[126:129]
	v_mfma_f32_16x16x32_bf16 v[122:125], v[170:173], v[186:189], v[122:125]
	v_mfma_f32_16x16x32_bf16 v[110:113], v[162:165], v[194:197], v[110:113]
	v_mfma_f32_16x16x32_bf16 v[106:109], v[170:173], v[194:197], v[106:109]
	v_mfma_f32_16x16x32_bf16 v[94:97], v[162:165], v[202:205], v[94:97]
	v_mfma_f32_16x16x32_bf16 v[90:93], v[170:173], v[202:205], v[90:93]
	v_mfma_f32_16x16x32_bf16 v[78:81], v[162:165], v[210:213], v[78:81]
	v_mfma_f32_16x16x32_bf16 v[74:77], v[170:173], v[210:213], v[74:77]
	s_setprio 0
	s_barrier
	s_add_i32 s27, 16, 0x14000
	s_add_i32 s26, s26, s18
	v_add_u32_e32 v151, s27, v148
	v_lshl_add_u64 v[152:153], s[4:5], 0, v[156:157]
	s_mov_b32 m0, s26
	ds_read_b128 v[214:217], v151
	ds_read_b128 v[218:221], v151 offset:1024
	ds_read_b128 v[222:225], v151 offset:2048
	ds_read_b128 v[226:229], v151 offset:3072
	global_load_lds_dwordx4 v[152:153], off
	v_lshl_add_u64 v[178:179], s[4:5], 0, v[160:161]
	s_add_i32 m0, s26, 0x2000
	s_nop 0
	global_load_lds_dwordx4 v[178:179], off
	s_barrier
	s_waitcnt lgkmcnt(0)
	s_setprio 1
	s_waitcnt lgkmcnt(0)
	v_mfma_f32_16x16x32_bf16 v[118:121], v[214:217], v[174:177], v[118:121]
	v_mfma_f32_16x16x32_bf16 v[114:117], v[222:225], v[174:177], v[114:117]
	v_mfma_f32_16x16x32_bf16 v[102:105], v[214:217], v[190:193], v[102:105]
	v_mfma_f32_16x16x32_bf16 v[98:101], v[222:225], v[190:193], v[98:101]
	v_mfma_f32_16x16x32_bf16 v[86:89], v[214:217], v[198:201], v[86:89]
	v_mfma_f32_16x16x32_bf16 v[82:85], v[222:225], v[198:201], v[82:85]
	v_mfma_f32_16x16x32_bf16 v[70:73], v[214:217], v[206:209], v[70:73]
	v_mfma_f32_16x16x32_bf16 v[66:69], v[222:225], v[206:209], v[66:69]
	v_mfma_f32_16x16x32_bf16 v[118:121], v[218:221], v[186:189], v[118:121]
	v_mfma_f32_16x16x32_bf16 v[114:117], v[226:229], v[186:189], v[114:117]
	v_mfma_f32_16x16x32_bf16 v[102:105], v[218:221], v[194:197], v[102:105]
	v_mfma_f32_16x16x32_bf16 v[98:101], v[226:229], v[194:197], v[98:101]
	v_mfma_f32_16x16x32_bf16 v[86:89], v[218:221], v[202:205], v[86:89]
	v_mfma_f32_16x16x32_bf16 v[82:85], v[226:229], v[202:205], v[82:85]
	v_mfma_f32_16x16x32_bf16 v[70:73], v[218:221], v[210:213], v[70:73]
	v_mfma_f32_16x16x32_bf16 v[66:69], v[226:229], v[210:213], v[66:69]
	s_setprio 0
	s_mov_b32 m0, s88
	v_lshl_add_u64 v[230:231], s[12:13], 0, v[154:155]
	s_barrier
	ds_read_b128 v[174:177], v150 offset:16384
	ds_read_b128 v[186:189], v150 offset:17408
	ds_read_b128 v[190:193], v150 offset:18432
	ds_read_b128 v[194:197], v150 offset:19456
	ds_read_b128 v[198:201], v150 offset:20480
	ds_read_b128 v[202:205], v150 offset:21504
	ds_read_b128 v[206:209], v150 offset:22528
	ds_read_b128 v[210:213], v150 offset:23552
	global_load_lds_dwordx4 v[230:231], off
	v_lshl_add_u64 v[242:243], s[12:13], 0, v[158:159]
	s_mov_b32 m0, s89
	s_nop 0
	global_load_lds_dwordx4 v[242:243], off
	s_barrier
	s_waitcnt lgkmcnt(0)
	s_setprio 1
	s_waitcnt lgkmcnt(0)
	v_mfma_f32_16x16x32_bf16 v[62:65], v[134:137], v[174:177], v[62:65]
	v_mfma_f32_16x16x32_bf16 v[58:61], v[166:169], v[174:177], v[58:61]
	v_mfma_f32_16x16x32_bf16 v[46:49], v[134:137], v[190:193], v[46:49]
	v_mfma_f32_16x16x32_bf16 v[42:45], v[166:169], v[190:193], v[42:45]
	v_mfma_f32_16x16x32_bf16 v[30:33], v[134:137], v[198:201], v[30:33]
	v_mfma_f32_16x16x32_bf16 v[26:29], v[166:169], v[198:201], v[26:29]
	v_mfma_f32_16x16x32_bf16 v[14:17], v[134:137], v[206:209], v[14:17]
	v_mfma_f32_16x16x32_bf16 v[10:13], v[166:169], v[206:209], v[10:13]
	v_mfma_f32_16x16x32_bf16 v[62:65], v[162:165], v[186:189], v[62:65]
	v_mfma_f32_16x16x32_bf16 v[58:61], v[170:173], v[186:189], v[58:61]
	v_mfma_f32_16x16x32_bf16 v[46:49], v[162:165], v[194:197], v[46:49]
	v_mfma_f32_16x16x32_bf16 v[42:45], v[170:173], v[194:197], v[42:45]
	v_mfma_f32_16x16x32_bf16 v[30:33], v[162:165], v[202:205], v[30:33]
	v_mfma_f32_16x16x32_bf16 v[26:29], v[170:173], v[202:205], v[26:29]
	v_mfma_f32_16x16x32_bf16 v[14:17], v[162:165], v[210:213], v[14:17]
	v_mfma_f32_16x16x32_bf16 v[10:13], v[170:173], v[210:213], v[10:13]
	s_setprio 0
	s_barrier
	s_add_u32 vcc_lo, s4, 0x80000
	s_addc_u32 vcc_hi, s5, 0
	s_add_i32 s26, s27, s18
	v_lshl_add_u64 v[134:135], vcc, 0, v[156:157]
	s_mov_b32 m0, s26
	s_nop 0
	global_load_lds_dwordx4 v[134:135], off
	v_lshl_add_u64 v[134:135], vcc, 0, v[160:161]
	s_add_i32 m0, s26, 0x2000
	s_nop 0
	global_load_lds_dwordx4 v[134:135], off
	s_waitcnt vmcnt(6)
	s_barrier
	s_setprio 1
	v_mfma_f32_16x16x32_bf16 v[54:57], v[214:217], v[174:177], v[54:57]
	v_mfma_f32_16x16x32_bf16 v[50:53], v[222:225], v[174:177], v[50:53]
	v_mfma_f32_16x16x32_bf16 v[38:41], v[214:217], v[190:193], v[38:41]
	v_mfma_f32_16x16x32_bf16 v[34:37], v[222:225], v[190:193], v[34:37]
	v_mfma_f32_16x16x32_bf16 v[22:25], v[214:217], v[198:201], v[22:25]
	v_mfma_f32_16x16x32_bf16 v[18:21], v[222:225], v[198:201], v[18:21]
	v_mfma_f32_16x16x32_bf16 v[6:9], v[214:217], v[206:209], v[6:9]
	v_mfma_f32_16x16x32_bf16 v[2:5], v[222:225], v[206:209], v[2:5]
	v_mfma_f32_16x16x32_bf16 v[54:57], v[218:221], v[186:189], v[54:57]
	v_mfma_f32_16x16x32_bf16 v[50:53], v[226:229], v[186:189], v[50:53]
	v_mfma_f32_16x16x32_bf16 v[38:41], v[218:221], v[194:197], v[38:41]
	v_mfma_f32_16x16x32_bf16 v[34:37], v[226:229], v[194:197], v[34:37]
	v_mfma_f32_16x16x32_bf16 v[22:25], v[218:221], v[202:205], v[22:25]
	v_mfma_f32_16x16x32_bf16 v[18:21], v[226:229], v[202:205], v[18:21]
	v_mfma_f32_16x16x32_bf16 v[6:9], v[218:221], v[210:213], v[6:9]
	v_mfma_f32_16x16x32_bf16 v[2:5], v[226:229], v[210:213], v[2:5]
	s_setprio 0
	s_add_i32 s26, 16, 0x18000
	v_add_u32_e32 v151, s26, v148
	s_barrier
	ds_read_b128 v[134:137], v151
	ds_read_b128 v[162:165], v151 offset:1024
	ds_read_b128 v[166:169], v151 offset:2048
	ds_read_b128 v[170:173], v151 offset:3072
	s_add_u32 s12, s12, 0x80000
	s_addc_u32 s13, s13, 0
	s_mov_b32 m0, s40
	v_lshl_add_u64 v[214:215], s[12:13], 0, v[154:155]
	ds_read_b128 v[174:177], v150 offset:32768
	ds_read_b128 v[186:189], v150 offset:33792
	ds_read_b128 v[190:193], v150 offset:34816
	ds_read_b128 v[194:197], v150 offset:35840
	ds_read_b128 v[198:201], v150 offset:36864
	ds_read_b128 v[202:205], v150 offset:37888
	ds_read_b128 v[206:209], v150 offset:38912
	ds_read_b128 v[210:213], v150 offset:39936
	global_load_lds_dwordx4 v[214:215], off
	v_lshl_add_u64 v[214:215], s[12:13], 0, v[158:159]
	s_mov_b32 m0, s41
	s_nop 0
	global_load_lds_dwordx4 v[214:215], off
	s_waitcnt lgkmcnt(8)
	s_barrier
	s_waitcnt lgkmcnt(0)
	s_setprio 1
	s_waitcnt lgkmcnt(0)
	v_mfma_f32_16x16x32_bf16 v[126:129], v[134:137], v[174:177], v[126:129]
	v_mfma_f32_16x16x32_bf16 v[122:125], v[166:169], v[174:177], v[122:125]
	v_mfma_f32_16x16x32_bf16 v[110:113], v[134:137], v[190:193], v[110:113]
	v_mfma_f32_16x16x32_bf16 v[106:109], v[166:169], v[190:193], v[106:109]
	v_mfma_f32_16x16x32_bf16 v[94:97], v[134:137], v[198:201], v[94:97]
	v_mfma_f32_16x16x32_bf16 v[90:93], v[166:169], v[198:201], v[90:93]
	v_mfma_f32_16x16x32_bf16 v[78:81], v[134:137], v[206:209], v[78:81]
	v_mfma_f32_16x16x32_bf16 v[74:77], v[166:169], v[206:209], v[74:77]
	v_mfma_f32_16x16x32_bf16 v[126:129], v[162:165], v[186:189], v[126:129]
	v_mfma_f32_16x16x32_bf16 v[122:125], v[170:173], v[186:189], v[122:125]
	v_mfma_f32_16x16x32_bf16 v[110:113], v[162:165], v[194:197], v[110:113]
	v_mfma_f32_16x16x32_bf16 v[106:109], v[170:173], v[194:197], v[106:109]
	v_mfma_f32_16x16x32_bf16 v[94:97], v[162:165], v[202:205], v[94:97]
	v_mfma_f32_16x16x32_bf16 v[90:93], v[170:173], v[202:205], v[90:93]
	v_mfma_f32_16x16x32_bf16 v[78:81], v[162:165], v[210:213], v[78:81]
	v_mfma_f32_16x16x32_bf16 v[74:77], v[170:173], v[210:213], v[74:77]
	s_setprio 0
	s_barrier
	s_add_i32 s12, 16, 0x1c000
	s_add_i32 s13, s26, s18
	v_add_u32_e32 v151, s12, v148
	v_lshl_add_u64 v[152:153], v[152:153], 0, s[92:93]
	s_mov_b32 m0, s13
	ds_read_b128 v[214:217], v151
	ds_read_b128 v[218:221], v151 offset:1024
	ds_read_b128 v[222:225], v151 offset:2048
	ds_read_b128 v[226:229], v151 offset:3072
	global_load_lds_dwordx4 v[152:153], off
	v_lshl_add_u64 v[152:153], v[178:179], 0, s[92:93]
	s_add_i32 m0, s13, 0x2000
	s_nop 0
	global_load_lds_dwordx4 v[152:153], off
	s_barrier
	s_waitcnt lgkmcnt(0)
	s_setprio 1
	s_waitcnt lgkmcnt(0)
	v_mfma_f32_16x16x32_bf16 v[118:121], v[214:217], v[174:177], v[118:121]
	v_mfma_f32_16x16x32_bf16 v[114:117], v[222:225], v[174:177], v[114:117]
	v_mfma_f32_16x16x32_bf16 v[102:105], v[214:217], v[190:193], v[102:105]
	v_mfma_f32_16x16x32_bf16 v[98:101], v[222:225], v[190:193], v[98:101]
	v_mfma_f32_16x16x32_bf16 v[86:89], v[214:217], v[198:201], v[86:89]
	v_mfma_f32_16x16x32_bf16 v[82:85], v[222:225], v[198:201], v[82:85]
	v_mfma_f32_16x16x32_bf16 v[70:73], v[214:217], v[206:209], v[70:73]
	v_mfma_f32_16x16x32_bf16 v[66:69], v[222:225], v[206:209], v[66:69]
	v_mfma_f32_16x16x32_bf16 v[118:121], v[218:221], v[186:189], v[118:121]
	v_mfma_f32_16x16x32_bf16 v[114:117], v[226:229], v[186:189], v[114:117]
	v_mfma_f32_16x16x32_bf16 v[102:105], v[218:221], v[194:197], v[102:105]
	v_mfma_f32_16x16x32_bf16 v[98:101], v[226:229], v[194:197], v[98:101]
	v_mfma_f32_16x16x32_bf16 v[86:89], v[218:221], v[202:205], v[86:89]
	v_mfma_f32_16x16x32_bf16 v[82:85], v[226:229], v[202:205], v[82:85]
	v_mfma_f32_16x16x32_bf16 v[70:73], v[218:221], v[210:213], v[70:73]
	v_mfma_f32_16x16x32_bf16 v[66:69], v[226:229], v[210:213], v[66:69]
	s_setprio 0
	s_mov_b32 m0, s19
	v_lshl_add_u64 v[152:153], v[230:231], 0, s[92:93]
	s_barrier
	ds_read_b128 v[174:177], v150 offset:49152
	ds_read_b128 v[186:189], v150 offset:50176
	ds_read_b128 v[190:193], v150 offset:51200
	ds_read_b128 v[194:197], v150 offset:52224
	ds_read_b128 v[198:201], v150 offset:53248
	ds_read_b128 v[202:205], v150 offset:54272
	ds_read_b128 v[206:209], v150 offset:55296
	ds_read_b128 v[210:213], v150 offset:56320
	global_load_lds_dwordx4 v[152:153], off
	v_lshl_add_u64 v[152:153], v[242:243], 0, s[92:93]
	s_mov_b32 m0, s64
	s_nop 0
	global_load_lds_dwordx4 v[152:153], off
	s_barrier
	s_waitcnt lgkmcnt(0)
	s_setprio 1
	s_waitcnt lgkmcnt(0)
	v_mfma_f32_16x16x32_bf16 v[62:65], v[134:137], v[174:177], v[62:65]
	v_mfma_f32_16x16x32_bf16 v[58:61], v[166:169], v[174:177], v[58:61]
	v_mfma_f32_16x16x32_bf16 v[46:49], v[134:137], v[190:193], v[46:49]
	v_mfma_f32_16x16x32_bf16 v[42:45], v[166:169], v[190:193], v[42:45]
	v_mfma_f32_16x16x32_bf16 v[30:33], v[134:137], v[198:201], v[30:33]
	v_mfma_f32_16x16x32_bf16 v[26:29], v[166:169], v[198:201], v[26:29]
	v_mfma_f32_16x16x32_bf16 v[14:17], v[134:137], v[206:209], v[14:17]
	v_mfma_f32_16x16x32_bf16 v[10:13], v[166:169], v[206:209], v[10:13]
	v_mfma_f32_16x16x32_bf16 v[62:65], v[162:165], v[186:189], v[62:65]
	v_mfma_f32_16x16x32_bf16 v[58:61], v[170:173], v[186:189], v[58:61]
	v_mfma_f32_16x16x32_bf16 v[46:49], v[162:165], v[194:197], v[46:49]
	v_mfma_f32_16x16x32_bf16 v[42:45], v[170:173], v[194:197], v[42:45]
	v_mfma_f32_16x16x32_bf16 v[30:33], v[162:165], v[202:205], v[30:33]
	v_mfma_f32_16x16x32_bf16 v[26:29], v[170:173], v[202:205], v[26:29]
	v_mfma_f32_16x16x32_bf16 v[14:17], v[162:165], v[210:213], v[14:17]
	v_mfma_f32_16x16x32_bf16 v[10:13], v[170:173], v[210:213], v[10:13]
	s_setprio 0
	s_barrier
	s_add_u32 s4, s4, 0x80080
	s_addc_u32 s5, s5, 0
	s_add_i32 s12, s12, s18
	v_lshl_add_u64 v[134:135], s[4:5], 0, v[156:157]
	s_mov_b32 m0, s12
	s_nop 0
	global_load_lds_dwordx4 v[134:135], off
	v_lshl_add_u64 v[134:135], s[4:5], 0, v[160:161]
	s_add_i32 m0, s12, 0x2000
	s_nop 0
	global_load_lds_dwordx4 v[134:135], off
	s_waitcnt vmcnt(6)
	s_barrier
	s_setprio 1
	v_mfma_f32_16x16x32_bf16 v[54:57], v[214:217], v[174:177], v[54:57]
	v_mfma_f32_16x16x32_bf16 v[50:53], v[222:225], v[174:177], v[50:53]
	v_mfma_f32_16x16x32_bf16 v[38:41], v[214:217], v[190:193], v[38:41]
	v_mfma_f32_16x16x32_bf16 v[34:37], v[222:225], v[190:193], v[34:37]
	v_mfma_f32_16x16x32_bf16 v[22:25], v[214:217], v[198:201], v[22:25]
	v_mfma_f32_16x16x32_bf16 v[18:21], v[222:225], v[198:201], v[18:21]
	v_mfma_f32_16x16x32_bf16 v[6:9], v[214:217], v[206:209], v[6:9]
	v_mfma_f32_16x16x32_bf16 v[2:5], v[222:225], v[206:209], v[2:5]
	v_mfma_f32_16x16x32_bf16 v[54:57], v[218:221], v[186:189], v[54:57]
	v_mfma_f32_16x16x32_bf16 v[50:53], v[226:229], v[186:189], v[50:53]
	v_mfma_f32_16x16x32_bf16 v[38:41], v[218:221], v[194:197], v[38:41]
	v_mfma_f32_16x16x32_bf16 v[34:37], v[226:229], v[194:197], v[34:37]
	v_mfma_f32_16x16x32_bf16 v[22:25], v[218:221], v[202:205], v[22:25]
	v_mfma_f32_16x16x32_bf16 v[18:21], v[226:229], v[202:205], v[18:21]
	v_mfma_f32_16x16x32_bf16 v[6:9], v[218:221], v[210:213], v[6:9]
	v_mfma_f32_16x16x32_bf16 v[2:5], v[226:229], v[210:213], v[2:5]
	s_setprio 0
	s_add_i32 s47, s47, 2
	s_add_u32 s0, s0, 0x100
	s_addc_u32 s1, s1, 0
	s_add_u32 s30, s30, 0x100
	s_addc_u32 s45, s45, 0
	s_cmp_gt_u32 s47, 29
	s_barrier
	s_cbranch_scc0 .LBB0_104
	v_lshl_add_u32 v134, s46, 8, v147
	v_ashrrev_i32_e32 v135, 31, v134
	v_readlane_b32 s4, v252, 24
	v_lshlrev_b64 v[162:163], 5, v[134:135]
	v_readlane_b32 s5, v252, 25
	v_lshlrev_b64 v[152:153], 12, v[134:135]
	s_mov_b32 s11, 0xf800000
	v_lshl_add_u64 v[166:167], s[4:5], 0, v[162:163]
	global_load_dwordx4 v[162:165], v[166:167], off
	s_nop 0
	global_load_dwordx4 v[166:169], v[166:167], off offset:16
	v_or_b32_e32 v176, 16, v134
	v_ashrrev_i32_e32 v177, 31, v176
	v_lshlrev_b64 v[176:177], 5, v[176:177]
	v_lshl_add_u64 v[176:177], s[4:5], 0, v[176:177]
	global_load_dwordx4 v[186:189], v[176:177], off
	global_load_dwordx4 v[190:193], v[176:177], off offset:16
	v_or_b32_e32 v176, 32, v134
	v_ashrrev_i32_e32 v177, 31, v176
	v_lshlrev_b64 v[176:177], 5, v[176:177]
	v_lshl_add_u64 v[176:177], s[4:5], 0, v[176:177]
	global_load_dwordx4 v[194:197], v[176:177], off
	global_load_dwordx4 v[198:201], v[176:177], off offset:16
	v_or_b32_e32 v176, 48, v134
	v_ashrrev_i32_e32 v177, 31, v176
	v_lshlrev_b64 v[176:177], 5, v[176:177]
	v_lshl_add_u64 v[176:177], s[4:5], 0, v[176:177]
	global_load_dwordx4 v[202:205], v[176:177], off
	global_load_dwordx4 v[206:209], v[176:177], off offset:16
	v_add_u32_e32 v176, 0x80, v134
	v_ashrrev_i32_e32 v177, 31, v176
	v_lshlrev_b64 v[176:177], 5, v[176:177]
	v_lshl_add_u64 v[176:177], s[4:5], 0, v[176:177]
	global_load_dwordx4 v[210:213], v[176:177], off
	global_load_dwordx4 v[214:217], v[176:177], off offset:16
	v_add_u32_e32 v176, 0x90, v134
	v_ashrrev_i32_e32 v177, 31, v176
	v_lshlrev_b64 v[176:177], 5, v[176:177]
	v_lshl_add_u64 v[176:177], s[4:5], 0, v[176:177]
	global_load_dwordx4 v[218:221], v[176:177], off
	global_load_dwordx4 v[222:225], v[176:177], off offset:16
	v_add_u32_e32 v176, 0xa0, v134
	v_ashrrev_i32_e32 v177, 31, v176
	v_lshlrev_b64 v[176:177], 5, v[176:177]
	v_lshl_add_u64 v[176:177], s[4:5], 0, v[176:177]
	global_load_dwordx4 v[226:229], v[176:177], off
	global_load_dwordx4 v[172:175], v[176:177], off offset:16
	v_lshl_or_b32 v136, s2, 8, v149
	v_readlane_b32 s2, v252, 20
	v_ashrrev_i32_e32 v137, 31, v136
	v_readlane_b32 s3, v252, 21
	v_lshlrev_b64 v[136:137], 1, v[136:137]
	s_mov_b64 s[12:13], s[28:29]
	v_lshl_add_u64 v[152:153], s[2:3], 0, v[152:153]
	v_lshl_add_u64 v[152:153], v[152:153], 0, v[136:137]
	s_mov_b32 s16, 0x1a000
	s_mov_b64 s[28:29], 0
	s_waitcnt vmcnt(0)
	v_mov_b32_e32 v170, v162
	v_mov_b32_e32 v171, v166
	v_mov_b32_e32 v166, v163
	v_pk_add_f32 v[162:163], v[170:171], v[166:167]
	v_mov_b32_e32 v166, v164
	v_mov_b32_e32 v167, v168
	v_mov_b32_e32 v168, v165
	v_pk_add_f32 v[164:165], v[166:167], v[168:169]
	s_nop 0
	v_pk_add_f32 v[162:163], v[162:163], v[164:165]
	s_nop 0
	v_add_f32_e32 v135, v162, v163
	v_fmamk_f32 v135, v135, 0x3a000000, v233
	v_cmp_gt_f32_e32 vcc, s11, v135
	v_mul_f32_e32 v151, 0x4f800000, v135
	s_nop 0
	v_cndmask_b32_e32 v135, v135, v151, vcc
	v_sqrt_f32_e32 v151, v135
	s_nop 0
	v_add_u32_e32 v162, -1, v151
	v_fma_f32 v163, -v162, v151, v135
	v_cmp_ge_f32_e64 s[46:47], 0, v163
	v_add_u32_e32 v163, 1, v151
	s_nop 0
	v_cndmask_b32_e64 v162, v151, v162, s[46:47]
	v_fma_f32 v151, -v163, v151, v135
	v_cmp_lt_f32_e64 s[46:47], 0, v151
	s_nop 1
	v_cndmask_b32_e64 v151, v162, v163, s[46:47]
	v_mul_f32_e32 v162, 0x37800000, v151
	v_cndmask_b32_e32 v151, v151, v162, vcc
	v_cmp_class_f32_e32 vcc, v135, v234
	s_nop 1
	v_cndmask_b32_e32 v135, v151, v135, vcc
	v_div_scale_f32 v151, s[0:1], v135, v135, 1.0
	v_rcp_f32_e32 v162, v151
	s_nop 0
	v_fma_f32 v163, -v151, v162, 1.0
	v_fmac_f32_e32 v162, v163, v162
	v_div_scale_f32 v163, vcc, 1.0, v135, 1.0
	v_mul_f32_e32 v164, v163, v162
	v_fma_f32 v165, -v151, v164, v163
	v_fmac_f32_e32 v164, v165, v162
	v_fma_f32 v151, -v151, v164, v163
	v_div_fmas_f32 v151, v151, v162, v164
	v_div_fixup_f32 v162, v151, v135, 1.0
	v_pk_mul_f32 v[128:129], v[128:129], v[162:163] op_sel_hi:[1,0]
	v_pk_mul_f32 v[126:127], v[126:127], v[162:163] op_sel_hi:[1,0]
	v_pk_mul_f32 v[164:165], v[124:125], v[162:163] op_sel_hi:[1,0]
	v_pk_mul_f32 v[124:125], v[122:123], v[162:163] op_sel_hi:[1,0]
	v_cvt_pk_bf16_f32 v122, v126, v127
	v_cvt_pk_bf16_f32 v123, v128, v129
	v_cvt_pk_bf16_f32 v124, v124, v125
	v_cvt_pk_bf16_f32 v125, v164, v165
	global_store_dwordx4 v[152:153], v[122:125], off
	v_pk_mul_f32 v[120:121], v[120:121], v[162:163] op_sel_hi:[1,0]
	v_pk_mul_f32 v[118:119], v[118:119], v[162:163] op_sel_hi:[1,0]
	v_pk_mul_f32 v[122:123], v[116:117], v[162:163] op_sel_hi:[1,0]
	v_pk_mul_f32 v[116:117], v[114:115], v[162:163] op_sel_hi:[1,0]
	v_cvt_pk_bf16_f32 v114, v118, v119
	v_cvt_pk_bf16_f32 v115, v120, v121
	v_cvt_pk_bf16_f32 v116, v116, v117
	v_cvt_pk_bf16_f32 v117, v122, v123
	global_store_dwordx4 v[152:153], v[114:117], off offset:256
	s_nop 1
	v_or_b32_e32 v116, 16, v134
	v_ashrrev_i32_e32 v117, 31, v116
	v_lshlrev_b64 v[114:115], 12, v[116:117]
	v_lshlrev_b64 v[116:117], 5, v[116:117]
	v_lshl_add_u64 v[120:121], s[4:5], 0, v[116:117]
	s_nop 0
	v_lshl_add_u64 v[114:115], s[2:3], 0, v[114:115]
	v_lshl_add_u64 v[114:115], v[114:115], 0, v[136:137]
	v_mov_b32_e32 v116, v186
	v_mov_b32_e32 v117, v187
	v_mov_b32_e32 v118, v188
	v_mov_b32_e32 v119, v189
	v_mov_b32_e32 v120, v190
	v_mov_b32_e32 v121, v191
	v_mov_b32_e32 v122, v192
	v_mov_b32_e32 v123, v193
	v_mov_b32_e32 v124, v116
	v_mov_b32_e32 v125, v120
	v_mov_b32_e32 v120, v117
	v_pk_add_f32 v[116:117], v[124:125], v[120:121]
	v_mov_b32_e32 v120, v118
	v_mov_b32_e32 v121, v122
	v_mov_b32_e32 v122, v119
	v_pk_add_f32 v[118:119], v[120:121], v[122:123]
	s_nop 0
	v_pk_add_f32 v[116:117], v[116:117], v[118:119]
	s_nop 0
	v_add_f32_e32 v116, v116, v117
	v_fmamk_f32 v116, v116, 0x3a000000, v233
	v_cmp_gt_f32_e32 vcc, s11, v116
	v_mul_f32_e32 v117, 0x4f800000, v116
	s_nop 0
	v_cndmask_b32_e32 v116, v116, v117, vcc
	v_sqrt_f32_e32 v117, v116
	s_nop 0
	v_add_u32_e32 v118, -1, v117
	v_fma_f32 v119, -v118, v117, v116
	v_cmp_ge_f32_e64 s[46:47], 0, v119
	v_add_u32_e32 v119, 1, v117
	s_nop 0
	v_cndmask_b32_e64 v118, v117, v118, s[46:47]
	v_fma_f32 v117, -v119, v117, v116
	v_cmp_lt_f32_e64 s[46:47], 0, v117
	s_nop 1
	v_cndmask_b32_e64 v117, v118, v119, s[46:47]
	v_mul_f32_e32 v118, 0x37800000, v117
	v_cndmask_b32_e32 v117, v117, v118, vcc
	v_cmp_class_f32_e32 vcc, v116, v234
	s_nop 1
	v_cndmask_b32_e32 v116, v117, v116, vcc
	v_div_scale_f32 v117, s[0:1], v116, v116, 1.0
	v_rcp_f32_e32 v118, v117
	s_nop 0
	v_fma_f32 v119, -v117, v118, 1.0
	v_fmac_f32_e32 v118, v119, v118
	v_div_scale_f32 v119, vcc, 1.0, v116, 1.0
	v_mul_f32_e32 v120, v119, v118
	v_fma_f32 v121, -v117, v120, v119
	v_fmac_f32_e32 v120, v121, v118
	v_fma_f32 v117, -v117, v120, v119
	v_div_fmas_f32 v117, v117, v118, v120
	v_div_fixup_f32 v116, v117, v116, 1.0
	v_pk_mul_f32 v[112:113], v[112:113], v[116:117] op_sel_hi:[1,0]
	v_pk_mul_f32 v[110:111], v[110:111], v[116:117] op_sel_hi:[1,0]
	v_pk_mul_f32 v[118:119], v[108:109], v[116:117] op_sel_hi:[1,0]
	v_pk_mul_f32 v[108:109], v[106:107], v[116:117] op_sel_hi:[1,0]
	v_cvt_pk_bf16_f32 v106, v110, v111
	v_cvt_pk_bf16_f32 v107, v112, v113
	v_cvt_pk_bf16_f32 v108, v108, v109
	v_cvt_pk_bf16_f32 v109, v118, v119
	global_store_dwordx4 v[114:115], v[106:109], off
	v_pk_mul_f32 v[104:105], v[104:105], v[116:117] op_sel_hi:[1,0]
	v_pk_mul_f32 v[102:103], v[102:103], v[116:117] op_sel_hi:[1,0]
	v_pk_mul_f32 v[106:107], v[100:101], v[116:117] op_sel_hi:[1,0]
	v_pk_mul_f32 v[100:101], v[98:99], v[116:117] op_sel_hi:[1,0]
	v_cvt_pk_bf16_f32 v98, v102, v103
	v_cvt_pk_bf16_f32 v99, v104, v105
	v_cvt_pk_bf16_f32 v100, v100, v101
	v_cvt_pk_bf16_f32 v101, v106, v107
	global_store_dwordx4 v[114:115], v[98:101], off offset:256
	s_nop 1
	v_or_b32_e32 v100, 32, v134
	v_ashrrev_i32_e32 v101, 31, v100
	v_lshlrev_b64 v[98:99], 12, v[100:101]
	v_lshlrev_b64 v[100:101], 5, v[100:101]
	v_lshl_add_u64 v[104:105], s[4:5], 0, v[100:101]
	s_nop 0
	v_lshl_add_u64 v[98:99], s[2:3], 0, v[98:99]
	v_lshl_add_u64 v[98:99], v[98:99], 0, v[136:137]
	v_mov_b32_e32 v100, v194
	v_mov_b32_e32 v101, v195
	v_mov_b32_e32 v102, v196
	v_mov_b32_e32 v103, v197
	v_mov_b32_e32 v104, v198
	v_mov_b32_e32 v105, v199
	v_mov_b32_e32 v106, v200
	v_mov_b32_e32 v107, v201
	v_mov_b32_e32 v108, v100
	v_mov_b32_e32 v109, v104
	v_mov_b32_e32 v104, v101
	v_pk_add_f32 v[100:101], v[108:109], v[104:105]
	v_mov_b32_e32 v104, v102
	v_mov_b32_e32 v105, v106
	v_mov_b32_e32 v106, v103
	v_pk_add_f32 v[102:103], v[104:105], v[106:107]
	s_nop 0
	v_pk_add_f32 v[100:101], v[100:101], v[102:103]
	s_nop 0
	v_add_f32_e32 v100, v100, v101
	v_fmamk_f32 v100, v100, 0x3a000000, v233
	v_cmp_gt_f32_e32 vcc, s11, v100
	v_mul_f32_e32 v101, 0x4f800000, v100
	s_nop 0
	v_cndmask_b32_e32 v100, v100, v101, vcc
	v_sqrt_f32_e32 v101, v100
	s_nop 0
	v_add_u32_e32 v102, -1, v101
	v_fma_f32 v103, -v102, v101, v100
	v_cmp_ge_f32_e64 s[46:47], 0, v103
	v_add_u32_e32 v103, 1, v101
	s_nop 0
	v_cndmask_b32_e64 v102, v101, v102, s[46:47]
	v_fma_f32 v101, -v103, v101, v100
	v_cmp_lt_f32_e64 s[46:47], 0, v101
	s_nop 1
	v_cndmask_b32_e64 v101, v102, v103, s[46:47]
	v_mul_f32_e32 v102, 0x37800000, v101
	v_cndmask_b32_e32 v101, v101, v102, vcc
	v_cmp_class_f32_e32 vcc, v100, v234
	s_nop 1
	v_cndmask_b32_e32 v100, v101, v100, vcc
	v_div_scale_f32 v101, s[0:1], v100, v100, 1.0
	v_rcp_f32_e32 v102, v101
	s_nop 0
	v_fma_f32 v103, -v101, v102, 1.0
	v_fmac_f32_e32 v102, v103, v102
	v_div_scale_f32 v103, vcc, 1.0, v100, 1.0
	v_mul_f32_e32 v104, v103, v102
	v_fma_f32 v105, -v101, v104, v103
	v_fmac_f32_e32 v104, v105, v102
	v_fma_f32 v101, -v101, v104, v103
	v_div_fmas_f32 v101, v101, v102, v104
	v_div_fixup_f32 v100, v101, v100, 1.0
	v_pk_mul_f32 v[96:97], v[96:97], v[100:101] op_sel_hi:[1,0]
	v_pk_mul_f32 v[94:95], v[94:95], v[100:101] op_sel_hi:[1,0]
	v_pk_mul_f32 v[102:103], v[92:93], v[100:101] op_sel_hi:[1,0]
	v_pk_mul_f32 v[92:93], v[90:91], v[100:101] op_sel_hi:[1,0]
	v_cvt_pk_bf16_f32 v90, v94, v95
	v_cvt_pk_bf16_f32 v91, v96, v97
	v_cvt_pk_bf16_f32 v92, v92, v93
	v_cvt_pk_bf16_f32 v93, v102, v103
	global_store_dwordx4 v[98:99], v[90:93], off
	v_pk_mul_f32 v[88:89], v[88:89], v[100:101] op_sel_hi:[1,0]
	v_pk_mul_f32 v[86:87], v[86:87], v[100:101] op_sel_hi:[1,0]
	v_pk_mul_f32 v[90:91], v[84:85], v[100:101] op_sel_hi:[1,0]
	v_pk_mul_f32 v[84:85], v[82:83], v[100:101] op_sel_hi:[1,0]
	v_cvt_pk_bf16_f32 v82, v86, v87
	v_cvt_pk_bf16_f32 v83, v88, v89
	v_cvt_pk_bf16_f32 v84, v84, v85
	v_cvt_pk_bf16_f32 v85, v90, v91
	global_store_dwordx4 v[98:99], v[82:85], off offset:256
	s_nop 1
	v_or_b32_e32 v84, 48, v134
	v_ashrrev_i32_e32 v85, 31, v84
	v_lshlrev_b64 v[82:83], 12, v[84:85]
	v_lshlrev_b64 v[84:85], 5, v[84:85]
	v_lshl_add_u64 v[88:89], s[4:5], 0, v[84:85]
	s_nop 0
	v_lshl_add_u64 v[82:83], s[2:3], 0, v[82:83]
	v_lshl_add_u64 v[82:83], v[82:83], 0, v[136:137]
	v_mov_b32_e32 v84, v202
	v_mov_b32_e32 v85, v203
	v_mov_b32_e32 v86, v204
	v_mov_b32_e32 v87, v205
	v_mov_b32_e32 v88, v206
	v_mov_b32_e32 v89, v207
	v_mov_b32_e32 v90, v208
	v_mov_b32_e32 v91, v209
	v_mov_b32_e32 v92, v84
	v_mov_b32_e32 v93, v88
	v_mov_b32_e32 v88, v85
	v_pk_add_f32 v[84:85], v[92:93], v[88:89]
	v_mov_b32_e32 v88, v86
	v_mov_b32_e32 v89, v90
	v_mov_b32_e32 v90, v87
	v_pk_add_f32 v[86:87], v[88:89], v[90:91]
	s_nop 0
	v_pk_add_f32 v[84:85], v[84:85], v[86:87]
	s_nop 0
	v_add_f32_e32 v84, v84, v85
	v_fmamk_f32 v84, v84, 0x3a000000, v233
	v_cmp_gt_f32_e32 vcc, s11, v84
	v_mul_f32_e32 v85, 0x4f800000, v84
	s_nop 0
	v_cndmask_b32_e32 v84, v84, v85, vcc
	v_sqrt_f32_e32 v85, v84
	s_nop 0
	v_add_u32_e32 v86, -1, v85
	v_fma_f32 v87, -v86, v85, v84
	v_cmp_ge_f32_e64 s[46:47], 0, v87
	v_add_u32_e32 v87, 1, v85
	s_nop 0
	v_cndmask_b32_e64 v86, v85, v86, s[46:47]
	v_fma_f32 v85, -v87, v85, v84
	v_cmp_lt_f32_e64 s[46:47], 0, v85
	s_nop 1
	v_cndmask_b32_e64 v85, v86, v87, s[46:47]
	v_mul_f32_e32 v86, 0x37800000, v85
	v_cndmask_b32_e32 v85, v85, v86, vcc
	v_cmp_class_f32_e32 vcc, v84, v234
	s_nop 1
	v_cndmask_b32_e32 v84, v85, v84, vcc
	v_div_scale_f32 v85, s[0:1], v84, v84, 1.0
	v_rcp_f32_e32 v86, v85
	s_nop 0
	v_fma_f32 v87, -v85, v86, 1.0
	v_fmac_f32_e32 v86, v87, v86
	v_div_scale_f32 v87, vcc, 1.0, v84, 1.0
	v_mul_f32_e32 v88, v87, v86
	v_fma_f32 v89, -v85, v88, v87
	v_fmac_f32_e32 v88, v89, v86
	v_fma_f32 v85, -v85, v88, v87
	v_div_fmas_f32 v85, v85, v86, v88
	v_div_fixup_f32 v84, v85, v84, 1.0
	v_pk_mul_f32 v[80:81], v[80:81], v[84:85] op_sel_hi:[1,0]
	v_pk_mul_f32 v[78:79], v[78:79], v[84:85] op_sel_hi:[1,0]
	v_pk_mul_f32 v[86:87], v[76:77], v[84:85] op_sel_hi:[1,0]
	v_pk_mul_f32 v[76:77], v[74:75], v[84:85] op_sel_hi:[1,0]
	v_cvt_pk_bf16_f32 v74, v78, v79
	v_cvt_pk_bf16_f32 v75, v80, v81
	v_cvt_pk_bf16_f32 v76, v76, v77
	v_cvt_pk_bf16_f32 v77, v86, v87
	global_store_dwordx4 v[82:83], v[74:77], off
	v_pk_mul_f32 v[72:73], v[72:73], v[84:85] op_sel_hi:[1,0]
	v_pk_mul_f32 v[70:71], v[70:71], v[84:85] op_sel_hi:[1,0]
	v_pk_mul_f32 v[74:75], v[68:69], v[84:85] op_sel_hi:[1,0]
	v_pk_mul_f32 v[68:69], v[66:67], v[84:85] op_sel_hi:[1,0]
	v_cvt_pk_bf16_f32 v66, v70, v71
	v_cvt_pk_bf16_f32 v67, v72, v73
	v_cvt_pk_bf16_f32 v68, v68, v69
	v_cvt_pk_bf16_f32 v69, v74, v75
	global_store_dwordx4 v[82:83], v[66:69], off offset:256
	s_nop 1
	v_add_u32_e32 v68, 0x80, v134
	v_ashrrev_i32_e32 v69, 31, v68
	v_lshlrev_b64 v[66:67], 12, v[68:69]
	v_lshlrev_b64 v[68:69], 5, v[68:69]
	v_lshl_add_u64 v[72:73], s[4:5], 0, v[68:69]
	s_nop 0
	v_lshl_add_u64 v[66:67], s[2:3], 0, v[66:67]
	v_lshl_add_u64 v[66:67], v[66:67], 0, v[136:137]
	v_mov_b32_e32 v68, v210
	v_mov_b32_e32 v69, v211
	v_mov_b32_e32 v70, v212
	v_mov_b32_e32 v71, v213
	v_mov_b32_e32 v72, v214
	v_mov_b32_e32 v73, v215
	v_mov_b32_e32 v74, v216
	v_mov_b32_e32 v75, v217
	v_mov_b32_e32 v76, v68
	v_mov_b32_e32 v77, v72
	v_mov_b32_e32 v72, v69
	v_pk_add_f32 v[68:69], v[76:77], v[72:73]
	v_mov_b32_e32 v72, v70
	v_mov_b32_e32 v73, v74
	v_mov_b32_e32 v74, v71
	v_pk_add_f32 v[70:71], v[72:73], v[74:75]
	s_nop 0
	v_pk_add_f32 v[68:69], v[68:69], v[70:71]
	s_nop 0
	v_add_f32_e32 v68, v68, v69
	v_fmamk_f32 v68, v68, 0x3a000000, v233
	v_cmp_gt_f32_e32 vcc, s11, v68
	v_mul_f32_e32 v69, 0x4f800000, v68
	s_nop 0
	v_cndmask_b32_e32 v68, v68, v69, vcc
	v_sqrt_f32_e32 v69, v68
	s_nop 0
	v_add_u32_e32 v70, -1, v69
	v_fma_f32 v71, -v70, v69, v68
	v_cmp_ge_f32_e64 s[46:47], 0, v71
	v_add_u32_e32 v71, 1, v69
	s_nop 0
	v_cndmask_b32_e64 v70, v69, v70, s[46:47]
	v_fma_f32 v69, -v71, v69, v68
	v_cmp_lt_f32_e64 s[46:47], 0, v69
	s_nop 1
	v_cndmask_b32_e64 v69, v70, v71, s[46:47]
	v_mul_f32_e32 v70, 0x37800000, v69
	v_cndmask_b32_e32 v69, v69, v70, vcc
	v_cmp_class_f32_e32 vcc, v68, v234
	s_nop 1
	v_cndmask_b32_e32 v68, v69, v68, vcc
	v_div_scale_f32 v69, s[0:1], v68, v68, 1.0
	v_rcp_f32_e32 v70, v69
	s_nop 0
	v_fma_f32 v71, -v69, v70, 1.0
	v_fmac_f32_e32 v70, v71, v70
	v_div_scale_f32 v71, vcc, 1.0, v68, 1.0
	v_mul_f32_e32 v72, v71, v70
	v_fma_f32 v73, -v69, v72, v71
	v_fmac_f32_e32 v72, v73, v70
	v_fma_f32 v69, -v69, v72, v71
	v_div_fmas_f32 v69, v69, v70, v72
	v_div_fixup_f32 v68, v69, v68, 1.0
	v_pk_mul_f32 v[64:65], v[64:65], v[68:69] op_sel_hi:[1,0]
	v_pk_mul_f32 v[62:63], v[62:63], v[68:69] op_sel_hi:[1,0]
	v_pk_mul_f32 v[70:71], v[60:61], v[68:69] op_sel_hi:[1,0]
	v_pk_mul_f32 v[60:61], v[58:59], v[68:69] op_sel_hi:[1,0]
	v_cvt_pk_bf16_f32 v58, v62, v63
	v_cvt_pk_bf16_f32 v59, v64, v65
	v_cvt_pk_bf16_f32 v60, v60, v61
	v_cvt_pk_bf16_f32 v61, v70, v71
	global_store_dwordx4 v[66:67], v[58:61], off
	v_pk_mul_f32 v[56:57], v[56:57], v[68:69] op_sel_hi:[1,0]
	v_pk_mul_f32 v[54:55], v[54:55], v[68:69] op_sel_hi:[1,0]
	v_pk_mul_f32 v[58:59], v[52:53], v[68:69] op_sel_hi:[1,0]
	v_pk_mul_f32 v[52:53], v[50:51], v[68:69] op_sel_hi:[1,0]
	v_cvt_pk_bf16_f32 v50, v54, v55
	v_cvt_pk_bf16_f32 v51, v56, v57
	v_cvt_pk_bf16_f32 v52, v52, v53
	v_cvt_pk_bf16_f32 v53, v58, v59
	global_store_dwordx4 v[66:67], v[50:53], off offset:256
	s_nop 1
	v_add_u32_e32 v52, 0x90, v134
	v_ashrrev_i32_e32 v53, 31, v52
	v_lshlrev_b64 v[50:51], 12, v[52:53]
	v_lshlrev_b64 v[52:53], 5, v[52:53]
	v_lshl_add_u64 v[56:57], s[4:5], 0, v[52:53]
	s_nop 0
	v_lshl_add_u64 v[50:51], s[2:3], 0, v[50:51]
	v_lshl_add_u64 v[50:51], v[50:51], 0, v[136:137]
	v_mov_b32_e32 v52, v218
	v_mov_b32_e32 v53, v219
	v_mov_b32_e32 v54, v220
	v_mov_b32_e32 v55, v221
	v_mov_b32_e32 v56, v222
	v_mov_b32_e32 v57, v223
	v_mov_b32_e32 v58, v224
	v_mov_b32_e32 v59, v225
	v_mov_b32_e32 v60, v52
	v_mov_b32_e32 v61, v56
	v_mov_b32_e32 v56, v53
	v_pk_add_f32 v[52:53], v[60:61], v[56:57]
	v_mov_b32_e32 v56, v54
	v_mov_b32_e32 v57, v58
	v_mov_b32_e32 v58, v55
	v_pk_add_f32 v[54:55], v[56:57], v[58:59]
	s_nop 0
	v_pk_add_f32 v[52:53], v[52:53], v[54:55]
	s_nop 0
	v_add_f32_e32 v52, v52, v53
	v_fmamk_f32 v52, v52, 0x3a000000, v233
	v_cmp_gt_f32_e32 vcc, s11, v52
	v_mul_f32_e32 v53, 0x4f800000, v52
	s_nop 0
	v_cndmask_b32_e32 v52, v52, v53, vcc
	v_sqrt_f32_e32 v53, v52
	s_nop 0
	v_add_u32_e32 v54, -1, v53
	v_fma_f32 v55, -v54, v53, v52
	v_cmp_ge_f32_e64 s[46:47], 0, v55
	v_add_u32_e32 v55, 1, v53
	s_nop 0
	v_cndmask_b32_e64 v54, v53, v54, s[46:47]
	v_fma_f32 v53, -v55, v53, v52
	v_cmp_lt_f32_e64 s[46:47], 0, v53
	s_nop 1
	v_cndmask_b32_e64 v53, v54, v55, s[46:47]
	v_mul_f32_e32 v54, 0x37800000, v53
	v_cndmask_b32_e32 v53, v53, v54, vcc
	v_cmp_class_f32_e32 vcc, v52, v234
	s_nop 1
	v_cndmask_b32_e32 v52, v53, v52, vcc
	v_div_scale_f32 v53, s[0:1], v52, v52, 1.0
	v_rcp_f32_e32 v54, v53
	s_nop 0
	v_fma_f32 v55, -v53, v54, 1.0
	v_fmac_f32_e32 v54, v55, v54
	v_div_scale_f32 v55, vcc, 1.0, v52, 1.0
	v_mul_f32_e32 v56, v55, v54
	v_fma_f32 v57, -v53, v56, v55
	v_fmac_f32_e32 v56, v57, v54
	v_fma_f32 v53, -v53, v56, v55
	v_div_fmas_f32 v53, v53, v54, v56
	v_div_fixup_f32 v52, v53, v52, 1.0
	v_pk_mul_f32 v[48:49], v[48:49], v[52:53] op_sel_hi:[1,0]
	v_pk_mul_f32 v[46:47], v[46:47], v[52:53] op_sel_hi:[1,0]
	v_pk_mul_f32 v[54:55], v[44:45], v[52:53] op_sel_hi:[1,0]
	v_pk_mul_f32 v[44:45], v[42:43], v[52:53] op_sel_hi:[1,0]
	v_cvt_pk_bf16_f32 v42, v46, v47
	v_cvt_pk_bf16_f32 v43, v48, v49
	v_cvt_pk_bf16_f32 v44, v44, v45
	v_cvt_pk_bf16_f32 v45, v54, v55
	global_store_dwordx4 v[50:51], v[42:45], off
	v_pk_mul_f32 v[40:41], v[40:41], v[52:53] op_sel_hi:[1,0]
	v_pk_mul_f32 v[38:39], v[38:39], v[52:53] op_sel_hi:[1,0]
	v_pk_mul_f32 v[42:43], v[36:37], v[52:53] op_sel_hi:[1,0]
	v_pk_mul_f32 v[36:37], v[34:35], v[52:53] op_sel_hi:[1,0]
	v_cvt_pk_bf16_f32 v34, v38, v39
	v_cvt_pk_bf16_f32 v35, v40, v41
	v_cvt_pk_bf16_f32 v36, v36, v37
	v_cvt_pk_bf16_f32 v37, v42, v43
	global_store_dwordx4 v[50:51], v[34:37], off offset:256
	s_nop 1
	v_add_u32_e32 v36, 0xa0, v134
	v_ashrrev_i32_e32 v37, 31, v36
	v_lshlrev_b64 v[34:35], 12, v[36:37]
	v_lshlrev_b64 v[36:37], 5, v[36:37]
	v_lshl_add_u64 v[40:41], s[4:5], 0, v[36:37]
	s_nop 0
	v_lshl_add_u64 v[34:35], s[2:3], 0, v[34:35]
	v_lshl_add_u64 v[34:35], v[34:35], 0, v[136:137]
	v_mov_b32_e32 v36, v226
	v_mov_b32_e32 v37, v227
	v_mov_b32_e32 v38, v228
	v_mov_b32_e32 v39, v229
	v_mov_b32_e32 v40, v172
	v_mov_b32_e32 v41, v173
	v_mov_b32_e32 v42, v174
	v_mov_b32_e32 v43, v175
	v_mov_b32_e32 v44, v36
	v_mov_b32_e32 v45, v40
	v_mov_b32_e32 v40, v37
	v_pk_add_f32 v[36:37], v[44:45], v[40:41]
	v_mov_b32_e32 v40, v38
	v_mov_b32_e32 v41, v42
	v_mov_b32_e32 v42, v39
	v_pk_add_f32 v[38:39], v[40:41], v[42:43]
	s_nop 0
	v_pk_add_f32 v[36:37], v[36:37], v[38:39]
	s_nop 0
	v_add_f32_e32 v36, v36, v37
	v_fmamk_f32 v36, v36, 0x3a000000, v233
	v_cmp_gt_f32_e32 vcc, s11, v36
	v_mul_f32_e32 v37, 0x4f800000, v36
	s_nop 0
	v_cndmask_b32_e32 v36, v36, v37, vcc
	v_sqrt_f32_e32 v37, v36
	s_nop 0
	v_add_u32_e32 v38, -1, v37
	v_fma_f32 v39, -v38, v37, v36
	v_cmp_ge_f32_e64 s[46:47], 0, v39
	v_add_u32_e32 v39, 1, v37
	s_nop 0
	v_cndmask_b32_e64 v38, v37, v38, s[46:47]
	v_fma_f32 v37, -v39, v37, v36
	v_cmp_lt_f32_e64 s[46:47], 0, v37
	s_nop 1
	v_cndmask_b32_e64 v37, v38, v39, s[46:47]
	v_mul_f32_e32 v38, 0x37800000, v37
	v_cndmask_b32_e32 v37, v37, v38, vcc
	v_cmp_class_f32_e32 vcc, v36, v234
	s_nop 1
	v_cndmask_b32_e32 v36, v37, v36, vcc
	v_div_scale_f32 v37, s[0:1], v36, v36, 1.0
	v_rcp_f32_e32 v38, v37
	s_nop 0
	v_fma_f32 v39, -v37, v38, 1.0
	v_fmac_f32_e32 v38, v39, v38
	v_div_scale_f32 v39, vcc, 1.0, v36, 1.0
	v_mul_f32_e32 v40, v39, v38
	v_fma_f32 v41, -v37, v40, v39
	v_fmac_f32_e32 v40, v41, v38
	v_fma_f32 v37, -v37, v40, v39
	v_div_fmas_f32 v37, v37, v38, v40
	v_div_fixup_f32 v36, v37, v36, 1.0
	v_pk_mul_f32 v[32:33], v[32:33], v[36:37] op_sel_hi:[1,0]
	v_pk_mul_f32 v[30:31], v[30:31], v[36:37] op_sel_hi:[1,0]
	v_pk_mul_f32 v[38:39], v[28:29], v[36:37] op_sel_hi:[1,0]
	v_pk_mul_f32 v[28:29], v[26:27], v[36:37] op_sel_hi:[1,0]
	v_cvt_pk_bf16_f32 v26, v30, v31
	v_cvt_pk_bf16_f32 v27, v32, v33
	v_cvt_pk_bf16_f32 v28, v28, v29
	v_cvt_pk_bf16_f32 v29, v38, v39
	global_store_dwordx4 v[34:35], v[26:29], off
	v_pk_mul_f32 v[24:25], v[24:25], v[36:37] op_sel_hi:[1,0]
	v_pk_mul_f32 v[22:23], v[22:23], v[36:37] op_sel_hi:[1,0]
	v_pk_mul_f32 v[26:27], v[20:21], v[36:37] op_sel_hi:[1,0]
	v_pk_mul_f32 v[20:21], v[18:19], v[36:37] op_sel_hi:[1,0]
	v_cvt_pk_bf16_f32 v18, v22, v23
	v_cvt_pk_bf16_f32 v19, v24, v25
	v_cvt_pk_bf16_f32 v20, v20, v21
	v_cvt_pk_bf16_f32 v21, v26, v27
	global_store_dwordx4 v[34:35], v[18:21], off offset:256
	s_nop 1
	v_add_u32_e32 v20, 0xb0, v134
	v_ashrrev_i32_e32 v21, 31, v20
	v_lshlrev_b64 v[18:19], 12, v[20:21]
	v_lshlrev_b64 v[20:21], 5, v[20:21]
	v_lshl_add_u64 v[24:25], s[4:5], 0, v[20:21]
	global_load_dwordx4 v[20:23], v[24:25], off
	s_nop 0
	global_load_dwordx4 v[24:27], v[24:25], off offset:16
	v_lshl_add_u64 v[18:19], s[2:3], 0, v[18:19]
	v_lshl_add_u64 v[18:19], v[18:19], 0, v[136:137]
	s_mov_b32 s2, s10
	s_waitcnt vmcnt(0)
	v_mov_b32_e32 v28, v20
	v_mov_b32_e32 v29, v24
	v_mov_b32_e32 v24, v21
	v_pk_add_f32 v[20:21], v[28:29], v[24:25]
	v_mov_b32_e32 v24, v22
	v_mov_b32_e32 v25, v26
	v_mov_b32_e32 v26, v23
	v_pk_add_f32 v[22:23], v[24:25], v[26:27]
	s_nop 0
	v_pk_add_f32 v[20:21], v[20:21], v[22:23]
	s_nop 0
	v_add_f32_e32 v20, v20, v21
	v_fmamk_f32 v20, v20, 0x3a000000, v233
	v_cmp_gt_f32_e32 vcc, s11, v20
	v_mul_f32_e32 v21, 0x4f800000, v20
	s_nop 0
	v_cndmask_b32_e32 v20, v20, v21, vcc
	v_sqrt_f32_e32 v21, v20
	s_nop 0
	v_add_u32_e32 v22, -1, v21
	v_fma_f32 v23, -v22, v21, v20
	v_cmp_ge_f32_e64 s[46:47], 0, v23
	v_add_u32_e32 v23, 1, v21
	s_nop 0
	v_cndmask_b32_e64 v22, v21, v22, s[46:47]
	v_fma_f32 v21, -v23, v21, v20
	v_cmp_lt_f32_e64 s[46:47], 0, v21
	s_nop 1
	v_cndmask_b32_e64 v21, v22, v23, s[46:47]
	v_mul_f32_e32 v22, 0x37800000, v21
	v_cndmask_b32_e32 v21, v21, v22, vcc
	v_cmp_class_f32_e32 vcc, v20, v234
	s_mov_b32 s46, s14
	s_nop 0
	v_cndmask_b32_e32 v20, v21, v20, vcc
	v_div_scale_f32 v21, s[0:1], v20, v20, 1.0
	v_rcp_f32_e32 v22, v21
	s_mov_b64 s[0:1], s[24:25]
	v_fma_f32 v23, -v21, v22, 1.0
	v_fmac_f32_e32 v22, v23, v22
	v_div_scale_f32 v23, vcc, 1.0, v20, 1.0
	v_mul_f32_e32 v24, v23, v22
	v_fma_f32 v25, -v21, v24, v23
	v_fmac_f32_e32 v24, v25, v22
	v_fma_f32 v21, -v21, v24, v23
	v_div_fmas_f32 v21, v21, v22, v24
	v_div_fixup_f32 v20, v21, v20, 1.0
	v_pk_mul_f32 v[16:17], v[16:17], v[20:21] op_sel_hi:[1,0]
	v_pk_mul_f32 v[14:15], v[14:15], v[20:21] op_sel_hi:[1,0]
	v_pk_mul_f32 v[22:23], v[12:13], v[20:21] op_sel_hi:[1,0]
	v_pk_mul_f32 v[12:13], v[10:11], v[20:21] op_sel_hi:[1,0]
	v_cvt_pk_bf16_f32 v10, v14, v15
	v_cvt_pk_bf16_f32 v11, v16, v17
	v_cvt_pk_bf16_f32 v12, v12, v13
	v_cvt_pk_bf16_f32 v13, v22, v23
	global_store_dwordx4 v[18:19], v[10:13], off
	v_pk_mul_f32 v[8:9], v[8:9], v[20:21] op_sel_hi:[1,0]
	v_pk_mul_f32 v[6:7], v[6:7], v[20:21] op_sel_hi:[1,0]
	v_pk_mul_f32 v[10:11], v[4:5], v[20:21] op_sel_hi:[1,0]
	v_pk_mul_f32 v[4:5], v[2:3], v[20:21] op_sel_hi:[1,0]
	v_cvt_pk_bf16_f32 v2, v6, v7
	v_cvt_pk_bf16_f32 v3, v8, v9
	v_cvt_pk_bf16_f32 v4, v4, v5
	v_cvt_pk_bf16_f32 v5, v10, v11
	s_and_b64 vcc, exec, s[42:43]
	global_store_dwordx4 v[18:19], v[2:5], off offset:256
	s_cbranch_vccz .LBB0_97
	s_waitcnt vmcnt(0)
	s_cmpk_gt_u32 s55, 0xff
	s_cbranch_scc1 .LBB0_108
	s_barrier
